# gate/up tiles: first two K-loop waits after an epilogue use vmcnt(16) so they do not wait for the 8 epilogue stores (in-order vmcnt); first tile keeps vmcnt(8)
# speedup vs baseline: 1.0055x; 1.0055x over previous
; #define PG8_STAGE(bufoff, gbase, voff) do { _Pragma("unroll") for (int _i = 0; _i < 2; ++_i) \
;         __builtin_amdgcn_global_load_lds((const unsigned*)((const char*)(gbase) + (voff)[_i]), (PG8_LAS unsigned*)(lds + (bufoff) + ldsw + _i * 8192), 16, 0, 0); } while (0)
; #define PG8_LDA(dst, b, h) do { _Pragma("unroll") for (int m = 0; m < 4; ++m) _Pragma("unroll") for (int k = 0; k < 2; ++k) dst[m][k] = *(const PG8_LAS bf16x8*)(lds + PG8_SA(b, h) + aoff + m * 2048 + k * 1024); } while (0)
; #define PG8_LDB(dst, b, h) do { _Pragma("unroll") for (int n = 0; n < 2; ++n) _Pragma("unroll") for (int k = 0; k < 2; ++k) dst[n][k] = *(const PG8_LAS bf16x8*)(lds + PG8_SB(b, h) + boff + n * 2048 + k * 1024); } while (0)
; #define PG8_WAIT_V(n) asm volatile("s_waitcnt vmcnt(" #n ")" ::: "memory")
; #define PG8_WAIT_L(n) asm volatile("s_waitcnt lgkmcnt(" #n ")" ::: "memory")
; #define PG8_BAR __builtin_amdgcn_s_barrier()
; #define PG8_SCHED __builtin_amdgcn_sched_barrier(0)
; template <class Epi, class Sched, bool ALIGN_EPI = false, bool SP2 = false, bool F16 = false, bool TOKPERM = false>
; __device__ __forceinline__ void gemm_phase(PG8_LAS unsigned char* lds, const Gemm g, const Sched& S, const Epi& E, int wv) {
;     ...
;         const bool has_next = S.next(ui + 1, nxt);
;         const char* nA = has_next ? (const char*)g.A + (size_t)nxt.pm * tstep : cA; const char* nB = has_next ? (const char*)g.Bt + (size_t)nxt.pn * tstep : cB;
;         for (int t = 0; t < nt; t += 2) {
;             const bool last = (t == nt - 2);
;             const char* a1 = cA + (size_t)(t + 1) * kstep;
;             const char* a2 = last ? nA : cA + (size_t)(t + 2) * kstep; const char* b2 = last ? nB : cB + (size_t)(t + 2) * kstep;
;             const char* a3 = a2 + kstep; const char* b3 = b2 + kstep;
;             if (last && has_next) S.a_ready(nxt);
;             if constexpr (SP2) {
;             PG8_LDB(B0, 0, 0); PG8_LDB(B1, 0, 1); PG8_SCHED; PG8_LDA(At, 0, 0); PG8_STAGE(PG8_SA(1, 1), a1 + hstep, voffA);
;             PG8_WAIT_V(8); PG8_WAIT_L(0); PG8_BAR; PG8_MMA(0, 0, At, B0); PG8_MMA(0, 1, At, B1); PG8_BAR; PG8_SCHED;
;             PG8_LDA(At, 0, 1); PG8_STAGE(PG8_SB(0, 0), b2, voffB); PG8_STAGE(PG8_SB(0, 1), b2 + hstep, voffB); PG8_STAGE(PG8_SA(0, 0), a2, voffA);
;             PG8_WAIT_V(8); PG8_WAIT_L(0); PG8_BAR; PG8_MMA(1, 0, At, B0); PG8_MMA(1, 1, At, B1); PG8_BAR; PG8_SCHED;
.LBB0_180:
	s_ashr_i32 s51, s50, 31
	s_lshl_b64 s[52:53], s[50:51], 19
	s_add_u32 s52, s40, s52
	s_addc_u32 s53, s41, s53
	s_and_b64 s[54:55], s[2:3], exec
	s_cselect_b32 s51, s53, s7
	s_cselect_b32 s77, s52, s6
	s_ashr_i32 s49, s48, 31
	s_lshl_b64 s[54:55], s[48:49], 19
	s_add_u32 s54, s33, s54
	s_addc_u32 s55, s36, s55
	s_and_b64 s[56:57], s[2:3], exec
	s_cselect_b32 s49, s55, s9
	s_cselect_b32 s78, s54, s8
	s_add_u32 s6, s6, 0x40080
	s_addc_u32 s7, s7, 0
	s_add_u32 s79, s8, 0x100
	s_addc_u32 s80, s9, 0
	s_mov_b32 s81, -2
	ds_read_b128 v[172:175], v155
	ds_read_b128 v[176:179], v156
	ds_read_b128 v[180:183], v157
	ds_read_b128 v[184:187], v158
	ds_read_b128 v[188:191], v159
	ds_read_b128 v[192:195], v160
	ds_read_b128 v[196:199], v161
	ds_read_b128 v[200:203], v162
	s_add_u32 s8, s6, 0xfffc0080
	s_addc_u32 s9, s7, -1
	s_cmp_eq_u32 s81, 12
	s_cselect_b32 s57, s51, s9
	s_cselect_b32 s56, s77, s8
	s_cselect_b32 s9, s49, s80
	s_cselect_b32 s8, s78, s79
	s_mov_b32 m0, s73
	v_lshl_add_u64 v[148:149], s[6:7], 0, v[140:141]
	ds_read_b128 v[204:207], v153
	ds_read_b128 v[208:211], v153 offset:1024
	ds_read_b128 v[212:215], v153 offset:2048
	ds_read_b128 v[216:219], v153 offset:3072
	ds_read_b128 v[220:223], v153 offset:4096
	ds_read_b128 v[228:231], v153 offset:5120
	ds_read_b128 v[232:235], v153 offset:6144
	ds_read_b128 v[236:239], v153 offset:7168
	global_load_lds_dwordx4 v[148:149], off
	v_lshl_add_u64 v[148:149], s[6:7], 0, v[142:143]
	s_mov_b32 m0, s74
	s_nop 0
	global_load_lds_dwordx4 v[148:149], off
	s_waitcnt vmcnt(16)
	s_cmp_lg_u32 s99, -1
	s_cbranch_scc1 .Lvmw_181_0
	s_waitcnt vmcnt(8)
.Lvmw_181_0:
	s_waitcnt lgkmcnt(0)
	s_barrier
	s_setprio 1
	s_waitcnt lgkmcnt(0)
	v_mfma_f32_16x16x32_f16 v[124:127], v[172:175], v[204:207], 0
	v_mfma_f32_16x16x32_f16 v[116:119], v[180:183], v[204:207], 0
	v_mfma_f32_16x16x32_f16 v[108:111], v[172:175], v[212:215], 0
	v_mfma_f32_16x16x32_f16 v[104:107], v[180:183], v[212:215], 0
	v_mfma_f32_16x16x32_f16 v[92:95], v[172:175], v[220:223], 0
	v_mfma_f32_16x16x32_f16 v[88:91], v[180:183], v[220:223], 0
	v_mfma_f32_16x16x32_f16 v[76:79], v[172:175], v[232:235], 0
	v_mfma_f32_16x16x32_f16 v[72:75], v[180:183], v[232:235], 0
	v_mfma_f32_16x16x32_f16 v[124:127], v[176:179], v[208:211], v[124:127]
	v_mfma_f32_16x16x32_f16 v[116:119], v[184:187], v[208:211], v[116:119]
	v_mfma_f32_16x16x32_f16 v[108:111], v[176:179], v[216:219], v[108:111]
	v_mfma_f32_16x16x32_f16 v[104:107], v[184:187], v[216:219], v[104:107]
	v_mfma_f32_16x16x32_f16 v[92:95], v[176:179], v[228:231], v[92:95]
	v_mfma_f32_16x16x32_f16 v[88:91], v[184:187], v[228:231], v[88:91]
	v_mfma_f32_16x16x32_f16 v[76:79], v[176:179], v[236:239], v[76:79]
	v_mfma_f32_16x16x32_f16 v[72:75], v[184:187], v[236:239], v[72:75]
	s_setprio 0
	s_setprio 1
	v_mfma_f32_16x16x32_f16 v[120:123], v[188:191], v[204:207], 0
	v_mfma_f32_16x16x32_f16 v[112:115], v[196:199], v[204:207], 0
	v_mfma_f32_16x16x32_f16 v[100:103], v[188:191], v[212:215], 0
	v_mfma_f32_16x16x32_f16 v[96:99], v[196:199], v[212:215], 0
	v_mfma_f32_16x16x32_f16 v[84:87], v[188:191], v[220:223], 0
	v_mfma_f32_16x16x32_f16 v[80:83], v[196:199], v[220:223], 0
	v_mfma_f32_16x16x32_f16 v[68:71], v[188:191], v[232:235], 0
	v_mfma_f32_16x16x32_f16 v[64:67], v[196:199], v[232:235], 0
	v_mfma_f32_16x16x32_f16 v[120:123], v[192:195], v[208:211], v[120:123]
	v_mfma_f32_16x16x32_f16 v[112:115], v[200:203], v[208:211], v[112:115]
	v_mfma_f32_16x16x32_f16 v[100:103], v[192:195], v[216:219], v[100:103]
	v_mfma_f32_16x16x32_f16 v[96:99], v[200:203], v[216:219], v[96:99]
	v_mfma_f32_16x16x32_f16 v[84:87], v[192:195], v[228:231], v[84:87]
	v_mfma_f32_16x16x32_f16 v[80:83], v[200:203], v[228:231], v[80:83]
	v_mfma_f32_16x16x32_f16 v[68:71], v[192:195], v[236:239], v[68:71]
	v_mfma_f32_16x16x32_f16 v[64:67], v[200:203], v[236:239], v[64:67]
	s_setprio 0
	s_barrier
	s_mov_b32 m0, s37
	v_lshl_add_u64 v[148:149], s[8:9], 0, v[132:133]
	s_add_u32 s82, s8, 0x40000
	ds_read_b128 v[204:207], v153 offset:16384
	ds_read_b128 v[208:211], v153 offset:17408
	ds_read_b128 v[212:215], v153 offset:18432
	ds_read_b128 v[216:219], v153 offset:19456
	ds_read_b128 v[220:223], v153 offset:20480
	ds_read_b128 v[228:231], v153 offset:21504
	ds_read_b128 v[232:235], v153 offset:22528
	ds_read_b128 v[236:239], v153 offset:23552
	global_load_lds_dwordx4 v[148:149], off
	v_lshl_add_u64 v[224:225], s[8:9], 0, v[128:129]
	s_mov_b32 m0, s45
	s_addc_u32 s83, s9, 0
	global_load_lds_dwordx4 v[224:225], off
	v_lshl_add_u64 v[240:241], s[82:83], 0, v[132:133]
	s_mov_b32 m0, s58
	v_lshl_add_u64 v[242:243], s[56:57], 0, v[130:131]
	global_load_lds_dwordx4 v[240:241], off
	v_lshl_add_u64 v[240:241], s[82:83], 0, v[128:129]
	s_mov_b32 m0, s59
	s_nop 0
	global_load_lds_dwordx4 v[240:241], off
	v_lshl_add_u64 v[240:241], s[56:57], 0, v[134:135]
	s_mov_b32 m0, s20
	s_nop 0
	global_load_lds_dwordx4 v[240:241], off
	s_mov_b32 m0, s60
	s_nop 0
	global_load_lds_dwordx4 v[242:243], off
	s_waitcnt vmcnt(16)
	s_cmp_lg_u32 s99, -1
	s_cbranch_scc1 .Lvmw_181_1
	s_waitcnt vmcnt(8)
; #define PG8_STAGE(bufoff, gbase, voff) do { _Pragma("unroll") for (int _i = 0; _i < 2; ++_i) \
;         __builtin_amdgcn_global_load_lds((const unsigned*)((const char*)(gbase) + (voff)[_i]), (PG8_LAS unsigned*)(lds + (bufoff) + ldsw + _i * 8192), 16, 0, 0); } while (0)
; #define PG8_LDA(dst, b, h) do { _Pragma("unroll") for (int m = 0; m < 4; ++m) _Pragma("unroll") for (int k = 0; k < 2; ++k) dst[m][k] = *(const PG8_LAS bf16x8*)(lds + PG8_SA(b, h) + aoff + m * 2048 + k * 1024); } while (0)
; #define PG8_LDB(dst, b, h) do { _Pragma("unroll") for (int n = 0; n < 2; ++n) _Pragma("unroll") for (int k = 0; k < 2; ++k) dst[n][k] = *(const PG8_LAS bf16x8*)(lds + PG8_SB(b, h) + boff + n * 2048 + k * 1024); } while (0)
; #define PG8_MMA(ai, bj, At, Bt) do { __builtin_amdgcn_s_setprio(1); _Pragma("unroll") for (int m = 0; m < 4; ++m) _Pragma("unroll") for (int n = 0; n < 2; ++n) _Pragma("unroll") for (int k = 0; k < 2; ++k) \
;         acc[ai][bj][m][n] = mma16<F16>(Bt[n][k], At[m][k], acc[ai][bj][m][n]); __builtin_amdgcn_s_setprio(0); } while (0)
; #define PG8_WAIT_V(n) asm volatile("s_waitcnt vmcnt(" #n ")" ::: "memory")
; #define PG8_WAIT_L(n) asm volatile("s_waitcnt lgkmcnt(" #n ")" ::: "memory")
; #define PG8_BAR __builtin_amdgcn_s_barrier()
; #define PG8_SCHED __builtin_amdgcn_sched_barrier(0)
; template <class Epi, class Sched, bool ALIGN_EPI = false, bool SP2 = false, bool F16 = false, bool TOKPERM = false>
; __device__ __forceinline__ void gemm_phase(PG8_LAS unsigned char* lds, const Gemm g, const Sched& S, const Epi& E, int wv) {
;     ...
;             PG8_WAIT_V(8); PG8_WAIT_L(0); PG8_BAR; PG8_MMA(1, 0, At, B0); PG8_MMA(1, 1, At, B1); PG8_BAR; PG8_SCHED;
;             PG8_LDB(B0, 1, 0); PG8_LDB(B1, 1, 1); PG8_SCHED; PG8_LDA(At, 1, 0); PG8_STAGE(PG8_SA(0, 1), a2 + hstep, voffA);
;             PG8_WAIT_V(8); PG8_WAIT_L(0); PG8_BAR; PG8_MMA(0, 0, At, B0); PG8_MMA(0, 1, At, B1); PG8_BAR; PG8_SCHED;
.Lvmw_181_1:
	s_waitcnt lgkmcnt(0)
	s_barrier
	s_setprio 1
	s_waitcnt lgkmcnt(0)
	v_mfma_f32_16x16x32_f16 v[60:63], v[172:175], v[204:207], 0
	v_mfma_f32_16x16x32_f16 v[56:59], v[180:183], v[204:207], 0
	v_mfma_f32_16x16x32_f16 v[44:47], v[172:175], v[212:215], 0
	v_mfma_f32_16x16x32_f16 v[40:43], v[180:183], v[212:215], 0
	v_mfma_f32_16x16x32_f16 v[28:31], v[172:175], v[220:223], 0
	v_mfma_f32_16x16x32_f16 v[24:27], v[180:183], v[220:223], 0
	v_mfma_f32_16x16x32_f16 v[12:15], v[172:175], v[232:235], 0
	v_mfma_f32_16x16x32_f16 v[8:11], v[180:183], v[232:235], 0
	v_mfma_f32_16x16x32_f16 v[60:63], v[176:179], v[208:211], v[60:63]
	v_mfma_f32_16x16x32_f16 v[56:59], v[184:187], v[208:211], v[56:59]
	v_mfma_f32_16x16x32_f16 v[44:47], v[176:179], v[216:219], v[44:47]
	v_mfma_f32_16x16x32_f16 v[40:43], v[184:187], v[216:219], v[40:43]
	v_mfma_f32_16x16x32_f16 v[28:31], v[176:179], v[228:231], v[28:31]
	v_mfma_f32_16x16x32_f16 v[24:27], v[184:187], v[228:231], v[24:27]
	v_mfma_f32_16x16x32_f16 v[12:15], v[176:179], v[236:239], v[12:15]
	v_mfma_f32_16x16x32_f16 v[8:11], v[184:187], v[236:239], v[8:11]
	s_setprio 0
	s_setprio 1
	v_mfma_f32_16x16x32_f16 v[52:55], v[188:191], v[204:207], 0
	v_mfma_f32_16x16x32_f16 v[48:51], v[196:199], v[204:207], 0
	v_mfma_f32_16x16x32_f16 v[36:39], v[188:191], v[212:215], 0
	v_mfma_f32_16x16x32_f16 v[32:35], v[196:199], v[212:215], 0
	v_mfma_f32_16x16x32_f16 v[20:23], v[188:191], v[220:223], 0
	v_mfma_f32_16x16x32_f16 v[16:19], v[196:199], v[220:223], 0
	v_mfma_f32_16x16x32_f16 v[4:7], v[188:191], v[232:235], 0
	v_mfma_f32_16x16x32_f16 v[0:3], v[196:199], v[232:235], 0
	v_mfma_f32_16x16x32_f16 v[52:55], v[192:195], v[208:211], v[52:55]
	v_mfma_f32_16x16x32_f16 v[48:51], v[200:203], v[208:211], v[48:51]
	v_mfma_f32_16x16x32_f16 v[36:39], v[192:195], v[216:219], v[36:39]
	v_mfma_f32_16x16x32_f16 v[32:35], v[200:203], v[216:219], v[32:35]
	v_mfma_f32_16x16x32_f16 v[20:23], v[192:195], v[228:231], v[20:23]
	v_mfma_f32_16x16x32_f16 v[16:19], v[200:203], v[228:231], v[16:19]
	v_mfma_f32_16x16x32_f16 v[4:7], v[192:195], v[236:239], v[4:7]
	v_mfma_f32_16x16x32_f16 v[0:3], v[200:203], v[236:239], v[0:3]
	s_setprio 0
	s_barrier
	ds_read_b128 v[172:175], v163
	ds_read_b128 v[176:179], v164
	ds_read_b128 v[180:183], v165
	ds_read_b128 v[184:187], v166
	ds_read_b128 v[188:191], v167
	ds_read_b128 v[192:195], v168
	ds_read_b128 v[196:199], v169
	ds_read_b128 v[200:203], v170
	s_add_u32 s56, s56, 0x40000
	s_addc_u32 s57, s57, 0
	s_mov_b32 m0, s61
	v_lshl_add_u64 v[244:245], s[56:57], 0, v[134:135]
	ds_read_b128 v[204:207], v153 offset:32768
	ds_read_b128 v[208:211], v153 offset:33792
	ds_read_b128 v[212:215], v153 offset:34816
	ds_read_b128 v[216:219], v153 offset:35840
	ds_read_b128 v[220:223], v153 offset:36864
	ds_read_b128 v[228:231], v153 offset:37888
	ds_read_b128 v[232:235], v153 offset:38912
	ds_read_b128 v[236:239], v153 offset:39936
	global_load_lds_dwordx4 v[244:245], off
	v_lshl_add_u64 v[244:245], s[56:57], 0, v[130:131]
	s_mov_b32 m0, s62
	s_nop 0
	global_load_lds_dwordx4 v[244:245], off
	s_waitcnt vmcnt(8)
	s_waitcnt lgkmcnt(0)
	s_barrier
	s_setprio 1
	s_waitcnt lgkmcnt(0)
	v_mfma_f32_16x16x32_f16 v[124:127], v[172:175], v[204:207], v[124:127]
	v_mfma_f32_16x16x32_f16 v[116:119], v[180:183], v[204:207], v[116:119]
	v_mfma_f32_16x16x32_f16 v[108:111], v[172:175], v[212:215], v[108:111]
	v_mfma_f32_16x16x32_f16 v[104:107], v[180:183], v[212:215], v[104:107]
	v_mfma_f32_16x16x32_f16 v[92:95], v[172:175], v[220:223], v[92:95]
	v_mfma_f32_16x16x32_f16 v[88:91], v[180:183], v[220:223], v[88:91]
	v_mfma_f32_16x16x32_f16 v[76:79], v[172:175], v[232:235], v[76:79]
	v_mfma_f32_16x16x32_f16 v[72:75], v[180:183], v[232:235], v[72:75]
	v_mfma_f32_16x16x32_f16 v[124:127], v[176:179], v[208:211], v[124:127]
	v_mfma_f32_16x16x32_f16 v[116:119], v[184:187], v[208:211], v[116:119]
	v_mfma_f32_16x16x32_f16 v[108:111], v[176:179], v[216:219], v[108:111]
	v_mfma_f32_16x16x32_f16 v[104:107], v[184:187], v[216:219], v[104:107]
	v_mfma_f32_16x16x32_f16 v[92:95], v[176:179], v[228:231], v[92:95]
	v_mfma_f32_16x16x32_f16 v[88:91], v[184:187], v[228:231], v[88:91]
	v_mfma_f32_16x16x32_f16 v[76:79], v[176:179], v[236:239], v[76:79]
	v_mfma_f32_16x16x32_f16 v[72:75], v[184:187], v[236:239], v[72:75]
	s_setprio 0
	s_setprio 1
	v_mfma_f32_16x16x32_f16 v[120:123], v[188:191], v[204:207], v[120:123]
	v_mfma_f32_16x16x32_f16 v[112:115], v[196:199], v[204:207], v[112:115]
	v_mfma_f32_16x16x32_f16 v[100:103], v[188:191], v[212:215], v[100:103]
	v_mfma_f32_16x16x32_f16 v[96:99], v[196:199], v[212:215], v[96:99]
	v_mfma_f32_16x16x32_f16 v[84:87], v[188:191], v[220:223], v[84:87]
	v_mfma_f32_16x16x32_f16 v[80:83], v[196:199], v[220:223], v[80:83]
	v_mfma_f32_16x16x32_f16 v[68:71], v[188:191], v[232:235], v[68:71]
	v_mfma_f32_16x16x32_f16 v[64:67], v[196:199], v[232:235], v[64:67]
	v_mfma_f32_16x16x32_f16 v[120:123], v[192:195], v[208:211], v[120:123]
	v_mfma_f32_16x16x32_f16 v[112:115], v[200:203], v[208:211], v[112:115]
	v_mfma_f32_16x16x32_f16 v[100:103], v[192:195], v[216:219], v[100:103]
	v_mfma_f32_16x16x32_f16 v[96:99], v[200:203], v[216:219], v[96:99]
	v_mfma_f32_16x16x32_f16 v[84:87], v[192:195], v[228:231], v[84:87]
	v_mfma_f32_16x16x32_f16 v[80:83], v[200:203], v[228:231], v[80:83]
	v_mfma_f32_16x16x32_f16 v[68:71], v[192:195], v[236:239], v[68:71]
	v_mfma_f32_16x16x32_f16 v[64:67], v[200:203], v[236:239], v[64:67]
	s_setprio 0
	s_barrier
; #define PG8_STAGE(bufoff, gbase, voff) do { _Pragma("unroll") for (int _i = 0; _i < 2; ++_i) \
;         __builtin_amdgcn_global_load_lds((const unsigned*)((const char*)(gbase) + (voff)[_i]), (PG8_LAS unsigned*)(lds + (bufoff) + ldsw + _i * 8192), 16, 0, 0); } while (0)
; #define PG8_LDA(dst, b, h) do { _Pragma("unroll") for (int m = 0; m < 4; ++m) _Pragma("unroll") for (int k = 0; k < 2; ++k) dst[m][k] = *(const PG8_LAS bf16x8*)(lds + PG8_SA(b, h) + aoff + m * 2048 + k * 1024); } while (0)
; #define PG8_MMA(ai, bj, At, Bt) do { __builtin_amdgcn_s_setprio(1); _Pragma("unroll") for (int m = 0; m < 4; ++m) _Pragma("unroll") for (int n = 0; n < 2; ++n) _Pragma("unroll") for (int k = 0; k < 2; ++k) \
;         acc[ai][bj][m][n] = mma16<F16>(Bt[n][k], At[m][k], acc[ai][bj][m][n]); __builtin_amdgcn_s_setprio(0); } while (0)
; #define PG8_WAIT_V(n) asm volatile("s_waitcnt vmcnt(" #n ")" ::: "memory")
; #define PG8_WAIT_L(n) asm volatile("s_waitcnt lgkmcnt(" #n ")" ::: "memory")
; #define PG8_BAR __builtin_amdgcn_s_barrier()
; #define PG8_SCHED __builtin_amdgcn_sched_barrier(0)
; template <class Epi, class Sched, bool ALIGN_EPI = false, bool SP2 = false, bool F16 = false, bool TOKPERM = false>
; __device__ __forceinline__ void gemm_phase(PG8_LAS unsigned char* lds, const Gemm g, const Sched& S, const Epi& E, int wv) {
;     ...
;             PG8_LDA(At, 1, 1); PG8_STAGE(PG8_SB(1, 0), b3, voffB); PG8_STAGE(PG8_SB(1, 1), b3 + hstep, voffB); PG8_STAGE(PG8_SA(1, 0), a3, voffA);
;             PG8_WAIT_V(8); PG8_WAIT_L(0); PG8_BAR; PG8_MMA(1, 0, At, B0); PG8_MMA(1, 1, At, B1); PG8_BAR; PG8_SCHED;
	s_mov_b32 m0, s64
	v_lshl_add_u64 v[148:149], v[148:149], 0, s[16:17]
	s_add_u32 s8, s8, 0x40080
	ds_read_b128 v[204:207], v153 offset:49152
	ds_read_b128 v[208:211], v153 offset:50176
	ds_read_b128 v[212:215], v153 offset:51200
	ds_read_b128 v[216:219], v153 offset:52224
	ds_read_b128 v[220:223], v153 offset:53248
	ds_read_b128 v[228:231], v153 offset:54272
	ds_read_b128 v[232:235], v153 offset:55296
	ds_read_b128 v[236:239], v153 offset:56320
	global_load_lds_dwordx4 v[148:149], off
	v_lshl_add_u64 v[148:149], v[224:225], 0, s[16:17]
	s_mov_b32 m0, s65
	s_addc_u32 s9, s9, 0
	global_load_lds_dwordx4 v[148:149], off
	v_lshl_add_u64 v[148:149], s[8:9], 0, v[132:133]
	s_mov_b32 m0, s69
	s_nop 0
	global_load_lds_dwordx4 v[148:149], off
	v_lshl_add_u64 v[148:149], s[8:9], 0, v[128:129]
	s_mov_b32 m0, s70
	s_nop 0
	global_load_lds_dwordx4 v[148:149], off
	v_lshl_add_u64 v[148:149], v[240:241], 0, s[16:17]
	s_mov_b32 m0, s66
	s_nop 0
	global_load_lds_dwordx4 v[148:149], off
	v_lshl_add_u64 v[148:149], v[242:243], 0, s[16:17]
	s_mov_b32 m0, s68
	s_nop 0
	global_load_lds_dwordx4 v[148:149], off
	s_waitcnt vmcnt(8)
	s_waitcnt lgkmcnt(0)
	s_barrier
	s_setprio 1
	s_waitcnt lgkmcnt(0)
	v_mfma_f32_16x16x32_f16 v[60:63], v[172:175], v[204:207], v[60:63]
	v_mfma_f32_16x16x32_f16 v[56:59], v[180:183], v[204:207], v[56:59]
	v_mfma_f32_16x16x32_f16 v[44:47], v[172:175], v[212:215], v[44:47]
	v_mfma_f32_16x16x32_f16 v[40:43], v[180:183], v[212:215], v[40:43]
	v_mfma_f32_16x16x32_f16 v[28:31], v[172:175], v[220:223], v[28:31]
	v_mfma_f32_16x16x32_f16 v[24:27], v[180:183], v[220:223], v[24:27]
	v_mfma_f32_16x16x32_f16 v[12:15], v[172:175], v[232:235], v[12:15]
	v_mfma_f32_16x16x32_f16 v[8:11], v[180:183], v[232:235], v[8:11]
	v_mfma_f32_16x16x32_f16 v[60:63], v[176:179], v[208:211], v[60:63]
	v_mfma_f32_16x16x32_f16 v[56:59], v[184:187], v[208:211], v[56:59]
	v_mfma_f32_16x16x32_f16 v[44:47], v[176:179], v[216:219], v[44:47]
	v_mfma_f32_16x16x32_f16 v[40:43], v[184:187], v[216:219], v[40:43]
	v_mfma_f32_16x16x32_f16 v[28:31], v[176:179], v[228:231], v[28:31]
	v_mfma_f32_16x16x32_f16 v[24:27], v[184:187], v[228:231], v[24:27]
	v_mfma_f32_16x16x32_f16 v[12:15], v[176:179], v[236:239], v[12:15]
	v_mfma_f32_16x16x32_f16 v[8:11], v[184:187], v[236:239], v[8:11]
	s_setprio 0
	s_setprio 1
	v_mfma_f32_16x16x32_f16 v[52:55], v[188:191], v[204:207], v[52:55]
	v_mfma_f32_16x16x32_f16 v[48:51], v[196:199], v[204:207], v[48:51]
	v_mfma_f32_16x16x32_f16 v[36:39], v[188:191], v[212:215], v[36:39]
	v_mfma_f32_16x16x32_f16 v[32:35], v[196:199], v[212:215], v[32:35]
	v_mfma_f32_16x16x32_f16 v[20:23], v[188:191], v[220:223], v[20:23]
	v_mfma_f32_16x16x32_f16 v[16:19], v[196:199], v[220:223], v[16:19]
	v_mfma_f32_16x16x32_f16 v[4:7], v[188:191], v[232:235], v[4:7]
	v_mfma_f32_16x16x32_f16 v[0:3], v[196:199], v[232:235], v[0:3]
	v_mfma_f32_16x16x32_f16 v[52:55], v[192:195], v[208:211], v[52:55]
	v_mfma_f32_16x16x32_f16 v[48:51], v[200:203], v[208:211], v[48:51]
	v_mfma_f32_16x16x32_f16 v[36:39], v[192:195], v[216:219], v[36:39]
	v_mfma_f32_16x16x32_f16 v[32:35], v[200:203], v[216:219], v[32:35]
	v_mfma_f32_16x16x32_f16 v[20:23], v[192:195], v[228:231], v[20:23]
	v_mfma_f32_16x16x32_f16 v[16:19], v[200:203], v[228:231], v[16:19]
	v_mfma_f32_16x16x32_f16 v[4:7], v[192:195], v[236:239], v[4:7]
	v_mfma_f32_16x16x32_f16 v[0:3], v[200:203], v[236:239], v[0:3]
	s_setprio 0
	s_barrier
	s_add_i32 s81, s81, 2
	s_add_u32 s6, s6, 0x100
	s_addc_u32 s7, s7, 0
	s_add_u32 s79, s79, 0x100
	s_addc_u32 s80, s80, 0
	s_cmp_gt_u32 s81, 13

; #define PG8_STAGE(bufoff, gbase, voff) do { _Pragma("unroll") for (int _i = 0; _i < 2; ++_i) \
;         __builtin_amdgcn_global_load_lds((const unsigned*)((const char*)(gbase) + (voff)[_i]), (PG8_LAS unsigned*)(lds + (bufoff) + ldsw + _i * 8192), 16, 0, 0); } while (0)
; #define PG8_LDA(dst, b, h) do { _Pragma("unroll") for (int m = 0; m < 4; ++m) _Pragma("unroll") for (int k = 0; k < 2; ++k) dst[m][k] = *(const PG8_LAS bf16x8*)(lds + PG8_SA(b, h) + aoff + m * 2048 + k * 1024); } while (0)
; #define PG8_LDB(dst, b, h) do { _Pragma("unroll") for (int n = 0; n < 2; ++n) _Pragma("unroll") for (int k = 0; k < 2; ++k) dst[n][k] = *(const PG8_LAS bf16x8*)(lds + PG8_SB(b, h) + boff + n * 2048 + k * 1024); } while (0)
; #define PG8_WAIT_V(n) asm volatile("s_waitcnt vmcnt(" #n ")" ::: "memory")
; #define PG8_WAIT_L(n) asm volatile("s_waitcnt lgkmcnt(" #n ")" ::: "memory")
; #define PG8_BAR __builtin_amdgcn_s_barrier()
; #define PG8_SCHED __builtin_amdgcn_sched_barrier(0)
; template <class Epi, class Sched, bool ALIGN_EPI = false, bool SP2 = false, bool F16 = false, bool TOKPERM = false>
; __device__ __forceinline__ void gemm_phase(PG8_LAS unsigned char* lds, const Gemm g, const Sched& S, const Epi& E, int wv) {
;     ...
;         const bool has_next = S.next(ui + 1, nxt);
;         const char* nA = has_next ? (const char*)g.A + (size_t)nxt.pm * tstep : cA; const char* nB = has_next ? (const char*)g.Bt + (size_t)nxt.pn * tstep : cB;
;         for (int t = 0; t < nt; t += 2) {
;             const bool last = (t == nt - 2);
;             const char* a1 = cA + (size_t)(t + 1) * kstep;
;             const char* a2 = last ? nA : cA + (size_t)(t + 2) * kstep; const char* b2 = last ? nB : cB + (size_t)(t + 2) * kstep;
;             const char* a3 = a2 + kstep; const char* b3 = b2 + kstep;
;             if (last && has_next) S.a_ready(nxt);
;             if constexpr (SP2) {
;             PG8_LDB(B0, 0, 0); PG8_LDB(B1, 0, 1); PG8_SCHED; PG8_LDA(At, 0, 0); PG8_STAGE(PG8_SA(1, 1), a1 + hstep, voffA);
;             PG8_WAIT_V(8); PG8_WAIT_L(0); PG8_BAR; PG8_MMA(0, 0, At, B0); PG8_MMA(0, 1, At, B1); PG8_BAR; PG8_SCHED;
;             PG8_LDA(At, 0, 1); PG8_STAGE(PG8_SB(0, 0), b2, voffB); PG8_STAGE(PG8_SB(0, 1), b2 + hstep, voffB); PG8_STAGE(PG8_SA(0, 0), a2, voffA);
;             PG8_WAIT_V(8); PG8_WAIT_L(0); PG8_BAR; PG8_MMA(1, 0, At, B0); PG8_MMA(1, 1, At, B1); PG8_BAR; PG8_SCHED;
.LBB0_767:
	s_ashr_i32 s53, s52, 31
	s_lshl_b64 s[54:55], s[52:53], 19
	s_add_u32 s54, s40, s54
	s_addc_u32 s55, s41, s55
	s_and_b64 s[56:57], s[6:7], exec
	s_cselect_b32 s53, s55, s11
	s_cselect_b32 s70, s54, s10
	s_ashr_i32 s51, s50, 31
	s_lshl_b64 s[56:57], s[50:51], 19
	s_add_u32 s56, s0, s56
	s_addc_u32 s57, s1, s57
	s_and_b64 s[58:59], s[6:7], exec
	s_cselect_b32 s51, s57, s13
	s_cselect_b32 s71, s56, s12
	s_add_u32 s10, s10, 0x40080
	s_addc_u32 s11, s11, 0
	s_add_u32 s72, s12, 0x100
	s_addc_u32 s73, s13, 0
	s_mov_b32 s74, -2
	ds_read_b128 v[172:175], v155
	ds_read_b128 v[176:179], v156
	ds_read_b128 v[180:183], v157
	ds_read_b128 v[184:187], v158
	ds_read_b128 v[188:191], v159
	ds_read_b128 v[192:195], v160
	ds_read_b128 v[196:199], v161
	ds_read_b128 v[200:203], v162
	s_add_u32 s12, s10, 0xfffc0080
	s_addc_u32 s13, s11, -1
	s_cmp_eq_u32 s74, 12
	s_cselect_b32 s59, s53, s13
	s_cselect_b32 s58, s70, s12
	s_cselect_b32 s13, s51, s73
	s_cselect_b32 s12, s71, s72
	s_mov_b32 m0, s66
	v_lshl_add_u64 v[148:149], s[10:11], 0, v[140:141]
	ds_read_b128 v[204:207], v153
	ds_read_b128 v[208:211], v153 offset:1024
	ds_read_b128 v[212:215], v153 offset:2048
	ds_read_b128 v[216:219], v153 offset:3072
	ds_read_b128 v[220:223], v153 offset:4096
	ds_read_b128 v[228:231], v153 offset:5120
	ds_read_b128 v[232:235], v153 offset:6144
	ds_read_b128 v[236:239], v153 offset:7168
	global_load_lds_dwordx4 v[148:149], off
	v_lshl_add_u64 v[148:149], s[10:11], 0, v[142:143]
	s_mov_b32 m0, s67
	s_nop 0
	global_load_lds_dwordx4 v[148:149], off
	s_waitcnt vmcnt(16)
	s_cmp_lg_u32 s99, -1
	s_cbranch_scc1 .Lvmw_768_0
	s_waitcnt vmcnt(8)
.Lvmw_768_0:
	s_waitcnt lgkmcnt(0)
	s_barrier
	s_setprio 1
	s_waitcnt lgkmcnt(0)
	v_mfma_f32_16x16x32_f16 v[124:127], v[172:175], v[204:207], 0
	v_mfma_f32_16x16x32_f16 v[116:119], v[180:183], v[204:207], 0
	v_mfma_f32_16x16x32_f16 v[108:111], v[172:175], v[212:215], 0
	v_mfma_f32_16x16x32_f16 v[104:107], v[180:183], v[212:215], 0
	v_mfma_f32_16x16x32_f16 v[92:95], v[172:175], v[220:223], 0
	v_mfma_f32_16x16x32_f16 v[88:91], v[180:183], v[220:223], 0
	v_mfma_f32_16x16x32_f16 v[76:79], v[172:175], v[232:235], 0
	v_mfma_f32_16x16x32_f16 v[72:75], v[180:183], v[232:235], 0
	v_mfma_f32_16x16x32_f16 v[124:127], v[176:179], v[208:211], v[124:127]
	v_mfma_f32_16x16x32_f16 v[116:119], v[184:187], v[208:211], v[116:119]
	v_mfma_f32_16x16x32_f16 v[108:111], v[176:179], v[216:219], v[108:111]
	v_mfma_f32_16x16x32_f16 v[104:107], v[184:187], v[216:219], v[104:107]
	v_mfma_f32_16x16x32_f16 v[92:95], v[176:179], v[228:231], v[92:95]
	v_mfma_f32_16x16x32_f16 v[88:91], v[184:187], v[228:231], v[88:91]
	v_mfma_f32_16x16x32_f16 v[76:79], v[176:179], v[236:239], v[76:79]
	v_mfma_f32_16x16x32_f16 v[72:75], v[184:187], v[236:239], v[72:75]
	s_setprio 0
	s_setprio 1
	v_mfma_f32_16x16x32_f16 v[120:123], v[188:191], v[204:207], 0
	v_mfma_f32_16x16x32_f16 v[112:115], v[196:199], v[204:207], 0
	v_mfma_f32_16x16x32_f16 v[100:103], v[188:191], v[212:215], 0
	v_mfma_f32_16x16x32_f16 v[96:99], v[196:199], v[212:215], 0
	v_mfma_f32_16x16x32_f16 v[84:87], v[188:191], v[220:223], 0
	v_mfma_f32_16x16x32_f16 v[80:83], v[196:199], v[220:223], 0
	v_mfma_f32_16x16x32_f16 v[68:71], v[188:191], v[232:235], 0
	v_mfma_f32_16x16x32_f16 v[64:67], v[196:199], v[232:235], 0
	v_mfma_f32_16x16x32_f16 v[120:123], v[192:195], v[208:211], v[120:123]
	v_mfma_f32_16x16x32_f16 v[112:115], v[200:203], v[208:211], v[112:115]
	v_mfma_f32_16x16x32_f16 v[100:103], v[192:195], v[216:219], v[100:103]
	v_mfma_f32_16x16x32_f16 v[96:99], v[200:203], v[216:219], v[96:99]
	v_mfma_f32_16x16x32_f16 v[84:87], v[192:195], v[228:231], v[84:87]
	v_mfma_f32_16x16x32_f16 v[80:83], v[200:203], v[228:231], v[80:83]
	v_mfma_f32_16x16x32_f16 v[68:71], v[192:195], v[236:239], v[68:71]
	v_mfma_f32_16x16x32_f16 v[64:67], v[200:203], v[236:239], v[64:67]
	s_setprio 0
	s_barrier
	s_mov_b32 m0, s5
	v_lshl_add_u64 v[148:149], s[12:13], 0, v[132:133]
	s_add_u32 s76, s12, 0x40000
	ds_read_b128 v[204:207], v153 offset:16384
	ds_read_b128 v[208:211], v153 offset:17408
	ds_read_b128 v[212:215], v153 offset:18432
	ds_read_b128 v[216:219], v153 offset:19456
	ds_read_b128 v[220:223], v153 offset:20480
	ds_read_b128 v[228:231], v153 offset:21504
	ds_read_b128 v[232:235], v153 offset:22528
	ds_read_b128 v[236:239], v153 offset:23552
	global_load_lds_dwordx4 v[148:149], off
	v_lshl_add_u64 v[224:225], s[12:13], 0, v[128:129]
	s_mov_b32 m0, s21
	s_addc_u32 s77, s13, 0
	global_load_lds_dwordx4 v[224:225], off
	v_lshl_add_u64 v[240:241], s[76:77], 0, v[132:133]
	s_mov_b32 m0, s22
	v_lshl_add_u64 v[242:243], s[58:59], 0, v[130:131]
	global_load_lds_dwordx4 v[240:241], off
	v_lshl_add_u64 v[240:241], s[76:77], 0, v[128:129]
	s_mov_b32 m0, s23
	s_nop 0
	global_load_lds_dwordx4 v[240:241], off
	v_lshl_add_u64 v[240:241], s[58:59], 0, v[134:135]
	s_mov_b32 m0, s2
	s_nop 0
	global_load_lds_dwordx4 v[240:241], off
	s_mov_b32 m0, s33
	s_nop 0
	global_load_lds_dwordx4 v[242:243], off
	s_waitcnt vmcnt(16)
	s_cmp_lg_u32 s99, -1
	s_cbranch_scc1 .Lvmw_768_1
	s_waitcnt vmcnt(8)
; #define PG8_STAGE(bufoff, gbase, voff) do { _Pragma("unroll") for (int _i = 0; _i < 2; ++_i) \
;         __builtin_amdgcn_global_load_lds((const unsigned*)((const char*)(gbase) + (voff)[_i]), (PG8_LAS unsigned*)(lds + (bufoff) + ldsw + _i * 8192), 16, 0, 0); } while (0)
; #define PG8_LDA(dst, b, h) do { _Pragma("unroll") for (int m = 0; m < 4; ++m) _Pragma("unroll") for (int k = 0; k < 2; ++k) dst[m][k] = *(const PG8_LAS bf16x8*)(lds + PG8_SA(b, h) + aoff + m * 2048 + k * 1024); } while (0)
; #define PG8_LDB(dst, b, h) do { _Pragma("unroll") for (int n = 0; n < 2; ++n) _Pragma("unroll") for (int k = 0; k < 2; ++k) dst[n][k] = *(const PG8_LAS bf16x8*)(lds + PG8_SB(b, h) + boff + n * 2048 + k * 1024); } while (0)
; #define PG8_MMA(ai, bj, At, Bt) do { __builtin_amdgcn_s_setprio(1); _Pragma("unroll") for (int m = 0; m < 4; ++m) _Pragma("unroll") for (int n = 0; n < 2; ++n) _Pragma("unroll") for (int k = 0; k < 2; ++k) \
;         acc[ai][bj][m][n] = mma16<F16>(Bt[n][k], At[m][k], acc[ai][bj][m][n]); __builtin_amdgcn_s_setprio(0); } while (0)
; #define PG8_WAIT_V(n) asm volatile("s_waitcnt vmcnt(" #n ")" ::: "memory")
; #define PG8_WAIT_L(n) asm volatile("s_waitcnt lgkmcnt(" #n ")" ::: "memory")
; #define PG8_BAR __builtin_amdgcn_s_barrier()
; #define PG8_SCHED __builtin_amdgcn_sched_barrier(0)
; template <class Epi, class Sched, bool ALIGN_EPI = false, bool SP2 = false, bool F16 = false, bool TOKPERM = false>
; __device__ __forceinline__ void gemm_phase(PG8_LAS unsigned char* lds, const Gemm g, const Sched& S, const Epi& E, int wv) {
;     ...
;             PG8_WAIT_V(8); PG8_WAIT_L(0); PG8_BAR; PG8_MMA(1, 0, At, B0); PG8_MMA(1, 1, At, B1); PG8_BAR; PG8_SCHED;
;             PG8_LDB(B0, 1, 0); PG8_LDB(B1, 1, 1); PG8_SCHED; PG8_LDA(At, 1, 0); PG8_STAGE(PG8_SA(0, 1), a2 + hstep, voffA);
;             PG8_WAIT_V(8); PG8_WAIT_L(0); PG8_BAR; PG8_MMA(0, 0, At, B0); PG8_MMA(0, 1, At, B1); PG8_BAR; PG8_SCHED;
.Lvmw_768_1:
	s_waitcnt lgkmcnt(0)
	s_barrier
	s_setprio 1
	s_waitcnt lgkmcnt(0)
	v_mfma_f32_16x16x32_f16 v[60:63], v[172:175], v[204:207], 0
	v_mfma_f32_16x16x32_f16 v[56:59], v[180:183], v[204:207], 0
	v_mfma_f32_16x16x32_f16 v[44:47], v[172:175], v[212:215], 0
	v_mfma_f32_16x16x32_f16 v[40:43], v[180:183], v[212:215], 0
	v_mfma_f32_16x16x32_f16 v[28:31], v[172:175], v[220:223], 0
	v_mfma_f32_16x16x32_f16 v[24:27], v[180:183], v[220:223], 0
	v_mfma_f32_16x16x32_f16 v[12:15], v[172:175], v[232:235], 0
	v_mfma_f32_16x16x32_f16 v[8:11], v[180:183], v[232:235], 0
	v_mfma_f32_16x16x32_f16 v[60:63], v[176:179], v[208:211], v[60:63]
	v_mfma_f32_16x16x32_f16 v[56:59], v[184:187], v[208:211], v[56:59]
	v_mfma_f32_16x16x32_f16 v[44:47], v[176:179], v[216:219], v[44:47]
	v_mfma_f32_16x16x32_f16 v[40:43], v[184:187], v[216:219], v[40:43]
	v_mfma_f32_16x16x32_f16 v[28:31], v[176:179], v[228:231], v[28:31]
	v_mfma_f32_16x16x32_f16 v[24:27], v[184:187], v[228:231], v[24:27]
	v_mfma_f32_16x16x32_f16 v[12:15], v[176:179], v[236:239], v[12:15]
	v_mfma_f32_16x16x32_f16 v[8:11], v[184:187], v[236:239], v[8:11]
	s_setprio 0
	s_setprio 1
	v_mfma_f32_16x16x32_f16 v[52:55], v[188:191], v[204:207], 0
	v_mfma_f32_16x16x32_f16 v[48:51], v[196:199], v[204:207], 0
	v_mfma_f32_16x16x32_f16 v[36:39], v[188:191], v[212:215], 0
	v_mfma_f32_16x16x32_f16 v[32:35], v[196:199], v[212:215], 0
	v_mfma_f32_16x16x32_f16 v[20:23], v[188:191], v[220:223], 0
	v_mfma_f32_16x16x32_f16 v[16:19], v[196:199], v[220:223], 0
	v_mfma_f32_16x16x32_f16 v[4:7], v[188:191], v[232:235], 0
	v_mfma_f32_16x16x32_f16 v[0:3], v[196:199], v[232:235], 0
	v_mfma_f32_16x16x32_f16 v[52:55], v[192:195], v[208:211], v[52:55]
	v_mfma_f32_16x16x32_f16 v[48:51], v[200:203], v[208:211], v[48:51]
	v_mfma_f32_16x16x32_f16 v[36:39], v[192:195], v[216:219], v[36:39]
	v_mfma_f32_16x16x32_f16 v[32:35], v[200:203], v[216:219], v[32:35]
	v_mfma_f32_16x16x32_f16 v[20:23], v[192:195], v[228:231], v[20:23]
	v_mfma_f32_16x16x32_f16 v[16:19], v[200:203], v[228:231], v[16:19]
	v_mfma_f32_16x16x32_f16 v[4:7], v[192:195], v[236:239], v[4:7]
	v_mfma_f32_16x16x32_f16 v[0:3], v[200:203], v[236:239], v[0:3]
	s_setprio 0
	s_barrier
	ds_read_b128 v[172:175], v163
	ds_read_b128 v[176:179], v164
	ds_read_b128 v[180:183], v165
	ds_read_b128 v[184:187], v166
	ds_read_b128 v[188:191], v167
	ds_read_b128 v[192:195], v168
	ds_read_b128 v[196:199], v169
	ds_read_b128 v[200:203], v170
	s_add_u32 s58, s58, 0x40000
	s_addc_u32 s59, s59, 0
	s_mov_b32 m0, s36
	v_lshl_add_u64 v[244:245], s[58:59], 0, v[134:135]
	ds_read_b128 v[204:207], v153 offset:32768
	ds_read_b128 v[208:211], v153 offset:33792
	ds_read_b128 v[212:215], v153 offset:34816
	ds_read_b128 v[216:219], v153 offset:35840
	ds_read_b128 v[220:223], v153 offset:36864
	ds_read_b128 v[228:231], v153 offset:37888
	ds_read_b128 v[232:235], v153 offset:38912
	ds_read_b128 v[236:239], v153 offset:39936
	global_load_lds_dwordx4 v[244:245], off
	v_lshl_add_u64 v[244:245], s[58:59], 0, v[130:131]
	s_mov_b32 m0, s37
	s_nop 0
	global_load_lds_dwordx4 v[244:245], off
	s_waitcnt vmcnt(8)
	s_waitcnt lgkmcnt(0)
	s_barrier
	s_setprio 1
	s_waitcnt lgkmcnt(0)
	v_mfma_f32_16x16x32_f16 v[124:127], v[172:175], v[204:207], v[124:127]
	v_mfma_f32_16x16x32_f16 v[116:119], v[180:183], v[204:207], v[116:119]
	v_mfma_f32_16x16x32_f16 v[108:111], v[172:175], v[212:215], v[108:111]
	v_mfma_f32_16x16x32_f16 v[104:107], v[180:183], v[212:215], v[104:107]
	v_mfma_f32_16x16x32_f16 v[92:95], v[172:175], v[220:223], v[92:95]
	v_mfma_f32_16x16x32_f16 v[88:91], v[180:183], v[220:223], v[88:91]
	v_mfma_f32_16x16x32_f16 v[76:79], v[172:175], v[232:235], v[76:79]
	v_mfma_f32_16x16x32_f16 v[72:75], v[180:183], v[232:235], v[72:75]
	v_mfma_f32_16x16x32_f16 v[124:127], v[176:179], v[208:211], v[124:127]
	v_mfma_f32_16x16x32_f16 v[116:119], v[184:187], v[208:211], v[116:119]
	v_mfma_f32_16x16x32_f16 v[108:111], v[176:179], v[216:219], v[108:111]
	v_mfma_f32_16x16x32_f16 v[104:107], v[184:187], v[216:219], v[104:107]
	v_mfma_f32_16x16x32_f16 v[92:95], v[176:179], v[228:231], v[92:95]
	v_mfma_f32_16x16x32_f16 v[88:91], v[184:187], v[228:231], v[88:91]
	v_mfma_f32_16x16x32_f16 v[76:79], v[176:179], v[236:239], v[76:79]
	v_mfma_f32_16x16x32_f16 v[72:75], v[184:187], v[236:239], v[72:75]
	s_setprio 0
	s_setprio 1
	v_mfma_f32_16x16x32_f16 v[120:123], v[188:191], v[204:207], v[120:123]
	v_mfma_f32_16x16x32_f16 v[112:115], v[196:199], v[204:207], v[112:115]
	v_mfma_f32_16x16x32_f16 v[100:103], v[188:191], v[212:215], v[100:103]
	v_mfma_f32_16x16x32_f16 v[96:99], v[196:199], v[212:215], v[96:99]
	v_mfma_f32_16x16x32_f16 v[84:87], v[188:191], v[220:223], v[84:87]
	v_mfma_f32_16x16x32_f16 v[80:83], v[196:199], v[220:223], v[80:83]
	v_mfma_f32_16x16x32_f16 v[68:71], v[188:191], v[232:235], v[68:71]
	v_mfma_f32_16x16x32_f16 v[64:67], v[196:199], v[232:235], v[64:67]
	v_mfma_f32_16x16x32_f16 v[120:123], v[192:195], v[208:211], v[120:123]
	v_mfma_f32_16x16x32_f16 v[112:115], v[200:203], v[208:211], v[112:115]
	v_mfma_f32_16x16x32_f16 v[100:103], v[192:195], v[216:219], v[100:103]
	v_mfma_f32_16x16x32_f16 v[96:99], v[200:203], v[216:219], v[96:99]
	v_mfma_f32_16x16x32_f16 v[84:87], v[192:195], v[228:231], v[84:87]
	v_mfma_f32_16x16x32_f16 v[80:83], v[200:203], v[228:231], v[80:83]
	v_mfma_f32_16x16x32_f16 v[68:71], v[192:195], v[236:239], v[68:71]
	v_mfma_f32_16x16x32_f16 v[64:67], v[200:203], v[236:239], v[64:67]
	s_setprio 0
	s_barrier
; #define PG8_STAGE(bufoff, gbase, voff) do { _Pragma("unroll") for (int _i = 0; _i < 2; ++_i) \
;         __builtin_amdgcn_global_load_lds((const unsigned*)((const char*)(gbase) + (voff)[_i]), (PG8_LAS unsigned*)(lds + (bufoff) + ldsw + _i * 8192), 16, 0, 0); } while (0)
; #define PG8_LDA(dst, b, h) do { _Pragma("unroll") for (int m = 0; m < 4; ++m) _Pragma("unroll") for (int k = 0; k < 2; ++k) dst[m][k] = *(const PG8_LAS bf16x8*)(lds + PG8_SA(b, h) + aoff + m * 2048 + k * 1024); } while (0)
; #define PG8_MMA(ai, bj, At, Bt) do { __builtin_amdgcn_s_setprio(1); _Pragma("unroll") for (int m = 0; m < 4; ++m) _Pragma("unroll") for (int n = 0; n < 2; ++n) _Pragma("unroll") for (int k = 0; k < 2; ++k) \
;         acc[ai][bj][m][n] = mma16<F16>(Bt[n][k], At[m][k], acc[ai][bj][m][n]); __builtin_amdgcn_s_setprio(0); } while (0)
; #define PG8_WAIT_V(n) asm volatile("s_waitcnt vmcnt(" #n ")" ::: "memory")
; #define PG8_WAIT_L(n) asm volatile("s_waitcnt lgkmcnt(" #n ")" ::: "memory")
; #define PG8_BAR __builtin_amdgcn_s_barrier()
; #define PG8_SCHED __builtin_amdgcn_sched_barrier(0)
; template <class Epi, class Sched, bool ALIGN_EPI = false, bool SP2 = false, bool F16 = false, bool TOKPERM = false>
; __device__ __forceinline__ void gemm_phase(PG8_LAS unsigned char* lds, const Gemm g, const Sched& S, const Epi& E, int wv) {
;     ...
;             PG8_LDA(At, 1, 1); PG8_STAGE(PG8_SB(1, 0), b3, voffB); PG8_STAGE(PG8_SB(1, 1), b3 + hstep, voffB); PG8_STAGE(PG8_SA(1, 0), a3, voffA);
;             PG8_WAIT_V(8); PG8_WAIT_L(0); PG8_BAR; PG8_MMA(1, 0, At, B0); PG8_MMA(1, 1, At, B1); PG8_BAR; PG8_SCHED;
	s_mov_b32 m0, s45
	v_lshl_add_u64 v[148:149], v[148:149], 0, s[16:17]
	s_add_u32 s12, s12, 0x40080
	ds_read_b128 v[204:207], v153 offset:49152
	ds_read_b128 v[208:211], v153 offset:50176
	ds_read_b128 v[212:215], v153 offset:51200
	ds_read_b128 v[216:219], v153 offset:52224
	ds_read_b128 v[220:223], v153 offset:53248
	ds_read_b128 v[228:231], v153 offset:54272
	ds_read_b128 v[232:235], v153 offset:55296
	ds_read_b128 v[236:239], v153 offset:56320
	global_load_lds_dwordx4 v[148:149], off
	v_lshl_add_u64 v[148:149], v[224:225], 0, s[16:17]
	s_mov_b32 m0, s49
	s_addc_u32 s13, s13, 0
	global_load_lds_dwordx4 v[148:149], off
	v_lshl_add_u64 v[148:149], s[12:13], 0, v[132:133]
	s_mov_b32 m0, s62
	s_nop 0
	global_load_lds_dwordx4 v[148:149], off
	v_lshl_add_u64 v[148:149], s[12:13], 0, v[128:129]
	s_mov_b32 m0, s63
	s_nop 0
	global_load_lds_dwordx4 v[148:149], off
	v_lshl_add_u64 v[148:149], v[240:241], 0, s[16:17]
	s_mov_b32 m0, s60
	s_nop 0
	global_load_lds_dwordx4 v[148:149], off
	v_lshl_add_u64 v[148:149], v[242:243], 0, s[16:17]
	s_mov_b32 m0, s61
	s_nop 0
	global_load_lds_dwordx4 v[148:149], off
	s_waitcnt vmcnt(8)
	s_waitcnt lgkmcnt(0)
	s_barrier
	s_setprio 1
	s_waitcnt lgkmcnt(0)
	v_mfma_f32_16x16x32_f16 v[60:63], v[172:175], v[204:207], v[60:63]
	v_mfma_f32_16x16x32_f16 v[56:59], v[180:183], v[204:207], v[56:59]
	v_mfma_f32_16x16x32_f16 v[44:47], v[172:175], v[212:215], v[44:47]
	v_mfma_f32_16x16x32_f16 v[40:43], v[180:183], v[212:215], v[40:43]
	v_mfma_f32_16x16x32_f16 v[28:31], v[172:175], v[220:223], v[28:31]
	v_mfma_f32_16x16x32_f16 v[24:27], v[180:183], v[220:223], v[24:27]
	v_mfma_f32_16x16x32_f16 v[12:15], v[172:175], v[232:235], v[12:15]
	v_mfma_f32_16x16x32_f16 v[8:11], v[180:183], v[232:235], v[8:11]
	v_mfma_f32_16x16x32_f16 v[60:63], v[176:179], v[208:211], v[60:63]
	v_mfma_f32_16x16x32_f16 v[56:59], v[184:187], v[208:211], v[56:59]
	v_mfma_f32_16x16x32_f16 v[44:47], v[176:179], v[216:219], v[44:47]
	v_mfma_f32_16x16x32_f16 v[40:43], v[184:187], v[216:219], v[40:43]
	v_mfma_f32_16x16x32_f16 v[28:31], v[176:179], v[228:231], v[28:31]
	v_mfma_f32_16x16x32_f16 v[24:27], v[184:187], v[228:231], v[24:27]
	v_mfma_f32_16x16x32_f16 v[12:15], v[176:179], v[236:239], v[12:15]
	v_mfma_f32_16x16x32_f16 v[8:11], v[184:187], v[236:239], v[8:11]
	s_setprio 0
	s_setprio 1
	v_mfma_f32_16x16x32_f16 v[52:55], v[188:191], v[204:207], v[52:55]
	v_mfma_f32_16x16x32_f16 v[48:51], v[196:199], v[204:207], v[48:51]
	v_mfma_f32_16x16x32_f16 v[36:39], v[188:191], v[212:215], v[36:39]
	v_mfma_f32_16x16x32_f16 v[32:35], v[196:199], v[212:215], v[32:35]
	v_mfma_f32_16x16x32_f16 v[20:23], v[188:191], v[220:223], v[20:23]
	v_mfma_f32_16x16x32_f16 v[16:19], v[196:199], v[220:223], v[16:19]
	v_mfma_f32_16x16x32_f16 v[4:7], v[188:191], v[232:235], v[4:7]
	v_mfma_f32_16x16x32_f16 v[0:3], v[196:199], v[232:235], v[0:3]
	v_mfma_f32_16x16x32_f16 v[52:55], v[192:195], v[208:211], v[52:55]
	v_mfma_f32_16x16x32_f16 v[48:51], v[200:203], v[208:211], v[48:51]
	v_mfma_f32_16x16x32_f16 v[36:39], v[192:195], v[216:219], v[36:39]
	v_mfma_f32_16x16x32_f16 v[32:35], v[200:203], v[216:219], v[32:35]
	v_mfma_f32_16x16x32_f16 v[20:23], v[192:195], v[228:231], v[20:23]
	v_mfma_f32_16x16x32_f16 v[16:19], v[200:203], v[228:231], v[16:19]
	v_mfma_f32_16x16x32_f16 v[4:7], v[192:195], v[236:239], v[4:7]
	v_mfma_f32_16x16x32_f16 v[0:3], v[200:203], v[236:239], v[0:3]
	s_setprio 0
	s_barrier
	s_add_i32 s74, s74, 2
	s_add_u32 s10, s10, 0x100
	s_addc_u32 s11, s11, 0
	s_add_u32 s72, s72, 0x100
	s_addc_u32 s73, s73, 0
	s_cmp_gt_u32 s74, 13

; #define PG8_STAGE(bufoff, gbase, voff) do { _Pragma("unroll") for (int _i = 0; _i < 2; ++_i) \
;         __builtin_amdgcn_global_load_lds((const unsigned*)((const char*)(gbase) + (voff)[_i]), (PG8_LAS unsigned*)(lds + (bufoff) + ldsw + _i * 8192), 16, 0, 0); } while (0)
; #define PG8_LDA(dst, b, h) do { _Pragma("unroll") for (int m = 0; m < 4; ++m) _Pragma("unroll") for (int k = 0; k < 2; ++k) dst[m][k] = *(const PG8_LAS bf16x8*)(lds + PG8_SA(b, h) + aoff + m * 2048 + k * 1024); } while (0)
; #define PG8_LDB(dst, b, h) do { _Pragma("unroll") for (int n = 0; n < 2; ++n) _Pragma("unroll") for (int k = 0; k < 2; ++k) dst[n][k] = *(const PG8_LAS bf16x8*)(lds + PG8_SB(b, h) + boff + n * 2048 + k * 1024); } while (0)
; #define PG8_WAIT_V(n) asm volatile("s_waitcnt vmcnt(" #n ")" ::: "memory")
; #define PG8_WAIT_L(n) asm volatile("s_waitcnt lgkmcnt(" #n ")" ::: "memory")
; #define PG8_BAR __builtin_amdgcn_s_barrier()
; #define PG8_SCHED __builtin_amdgcn_sched_barrier(0)
; template <class Epi, class Sched, bool ALIGN_EPI = false, bool SP2 = false, bool F16 = false, bool TOKPERM = false>
; __device__ __forceinline__ void gemm_phase(PG8_LAS unsigned char* lds, const Gemm g, const Sched& S, const Epi& E, int wv) {
;     ...
;         const bool has_next = S.next(ui + 1, nxt);
;         const char* nA = has_next ? (const char*)g.A + (size_t)nxt.pm * tstep : cA; const char* nB = has_next ? (const char*)g.Bt + (size_t)nxt.pn * tstep : cB;
;         for (int t = 0; t < nt; t += 2) {
;             const bool last = (t == nt - 2);
;             const char* a1 = cA + (size_t)(t + 1) * kstep;
;             const char* a2 = last ? nA : cA + (size_t)(t + 2) * kstep; const char* b2 = last ? nB : cB + (size_t)(t + 2) * kstep;
;             const char* a3 = a2 + kstep; const char* b3 = b2 + kstep;
;             if (last && has_next) S.a_ready(nxt);
;             if constexpr (SP2) {
;             PG8_LDB(B0, 0, 0); PG8_LDB(B1, 0, 1); PG8_SCHED; PG8_LDA(At, 0, 0); PG8_STAGE(PG8_SA(1, 1), a1 + hstep, voffA);
;             PG8_WAIT_V(8); PG8_WAIT_L(0); PG8_BAR; PG8_MMA(0, 0, At, B0); PG8_MMA(0, 1, At, B1); PG8_BAR; PG8_SCHED;
;             PG8_LDA(At, 0, 1); PG8_STAGE(PG8_SB(0, 0), b2, voffB); PG8_STAGE(PG8_SB(0, 1), b2 + hstep, voffB); PG8_STAGE(PG8_SA(0, 0), a2, voffA);
;             PG8_WAIT_V(8); PG8_WAIT_L(0); PG8_BAR; PG8_MMA(1, 0, At, B0); PG8_MMA(1, 1, At, B1); PG8_BAR; PG8_SCHED;
.LBB0_949:
	s_ashr_i32 s51, s50, 31
	s_lshl_b64 s[52:53], s[50:51], 19
	s_add_u32 s52, s40, s52
	s_addc_u32 s53, s41, s53
	s_and_b64 s[54:55], s[6:7], exec
	s_cselect_b32 s51, s53, s11
	s_cselect_b32 s70, s52, s10
	s_ashr_i32 s49, s48, 31
	s_lshl_b64 s[54:55], s[48:49], 19
	s_add_u32 s54, s0, s54
	s_addc_u32 s55, s1, s55
	s_and_b64 s[56:57], s[6:7], exec
	s_cselect_b32 s49, s55, s13
	s_cselect_b32 s71, s54, s12
	s_add_u32 s10, s10, 0x40080
	s_addc_u32 s11, s11, 0
	s_add_u32 s72, s12, 0x100
	s_addc_u32 s73, s13, 0
	s_mov_b32 s74, -2
	ds_read_b128 v[172:175], v155
	ds_read_b128 v[176:179], v156
	ds_read_b128 v[180:183], v157
	ds_read_b128 v[184:187], v158
	ds_read_b128 v[188:191], v159
	ds_read_b128 v[192:195], v160
	ds_read_b128 v[196:199], v161
	ds_read_b128 v[200:203], v162
	s_add_u32 s12, s10, 0xfffc0080
	s_addc_u32 s13, s11, -1
	s_cmp_eq_u32 s74, 12
	s_cselect_b32 s57, s51, s13
	s_cselect_b32 s56, s70, s12
	s_cselect_b32 s13, s49, s73
	s_cselect_b32 s12, s71, s72
	s_mov_b32 m0, s66
	v_lshl_add_u64 v[148:149], s[10:11], 0, v[140:141]
	ds_read_b128 v[204:207], v153
	ds_read_b128 v[208:211], v153 offset:1024
	ds_read_b128 v[212:215], v153 offset:2048
	ds_read_b128 v[216:219], v153 offset:3072
	ds_read_b128 v[220:223], v153 offset:4096
	ds_read_b128 v[228:231], v153 offset:5120
	ds_read_b128 v[232:235], v153 offset:6144
	ds_read_b128 v[236:239], v153 offset:7168
	global_load_lds_dwordx4 v[148:149], off
	v_lshl_add_u64 v[148:149], s[10:11], 0, v[142:143]
	s_mov_b32 m0, s67
	s_nop 0
	global_load_lds_dwordx4 v[148:149], off
	s_waitcnt vmcnt(16)
	s_cmp_lg_u32 s99, -1
	s_cbranch_scc1 .Lvmw_950_0
	s_waitcnt vmcnt(8)
.Lvmw_950_0:
	s_waitcnt lgkmcnt(0)
	s_barrier
	s_setprio 1
	s_waitcnt lgkmcnt(0)
	v_mfma_f32_16x16x32_f16 v[124:127], v[172:175], v[204:207], 0
	v_mfma_f32_16x16x32_f16 v[116:119], v[180:183], v[204:207], 0
	v_mfma_f32_16x16x32_f16 v[108:111], v[172:175], v[212:215], 0
	v_mfma_f32_16x16x32_f16 v[104:107], v[180:183], v[212:215], 0
	v_mfma_f32_16x16x32_f16 v[92:95], v[172:175], v[220:223], 0
	v_mfma_f32_16x16x32_f16 v[88:91], v[180:183], v[220:223], 0
	v_mfma_f32_16x16x32_f16 v[76:79], v[172:175], v[232:235], 0
	v_mfma_f32_16x16x32_f16 v[72:75], v[180:183], v[232:235], 0
	v_mfma_f32_16x16x32_f16 v[124:127], v[176:179], v[208:211], v[124:127]
	v_mfma_f32_16x16x32_f16 v[116:119], v[184:187], v[208:211], v[116:119]
	v_mfma_f32_16x16x32_f16 v[108:111], v[176:179], v[216:219], v[108:111]
	v_mfma_f32_16x16x32_f16 v[104:107], v[184:187], v[216:219], v[104:107]
	v_mfma_f32_16x16x32_f16 v[92:95], v[176:179], v[228:231], v[92:95]
	v_mfma_f32_16x16x32_f16 v[88:91], v[184:187], v[228:231], v[88:91]
	v_mfma_f32_16x16x32_f16 v[76:79], v[176:179], v[236:239], v[76:79]
	v_mfma_f32_16x16x32_f16 v[72:75], v[184:187], v[236:239], v[72:75]
	s_setprio 0
	s_setprio 1
	v_mfma_f32_16x16x32_f16 v[120:123], v[188:191], v[204:207], 0
	v_mfma_f32_16x16x32_f16 v[112:115], v[196:199], v[204:207], 0
	v_mfma_f32_16x16x32_f16 v[100:103], v[188:191], v[212:215], 0
	v_mfma_f32_16x16x32_f16 v[96:99], v[196:199], v[212:215], 0
	v_mfma_f32_16x16x32_f16 v[84:87], v[188:191], v[220:223], 0
	v_mfma_f32_16x16x32_f16 v[80:83], v[196:199], v[220:223], 0
	v_mfma_f32_16x16x32_f16 v[68:71], v[188:191], v[232:235], 0
	v_mfma_f32_16x16x32_f16 v[64:67], v[196:199], v[232:235], 0
	v_mfma_f32_16x16x32_f16 v[120:123], v[192:195], v[208:211], v[120:123]
	v_mfma_f32_16x16x32_f16 v[112:115], v[200:203], v[208:211], v[112:115]
	v_mfma_f32_16x16x32_f16 v[100:103], v[192:195], v[216:219], v[100:103]
	v_mfma_f32_16x16x32_f16 v[96:99], v[200:203], v[216:219], v[96:99]
	v_mfma_f32_16x16x32_f16 v[84:87], v[192:195], v[228:231], v[84:87]
	v_mfma_f32_16x16x32_f16 v[80:83], v[200:203], v[228:231], v[80:83]
	v_mfma_f32_16x16x32_f16 v[68:71], v[192:195], v[236:239], v[68:71]
	v_mfma_f32_16x16x32_f16 v[64:67], v[200:203], v[236:239], v[64:67]
	s_setprio 0
	s_barrier
	s_mov_b32 m0, s5
	v_lshl_add_u64 v[148:149], s[12:13], 0, v[132:133]
	s_add_u32 s76, s12, 0x40000
	ds_read_b128 v[204:207], v153 offset:16384
	ds_read_b128 v[208:211], v153 offset:17408
	ds_read_b128 v[212:215], v153 offset:18432
	ds_read_b128 v[216:219], v153 offset:19456
	ds_read_b128 v[220:223], v153 offset:20480
	ds_read_b128 v[228:231], v153 offset:21504
	ds_read_b128 v[232:235], v153 offset:22528
	ds_read_b128 v[236:239], v153 offset:23552
	global_load_lds_dwordx4 v[148:149], off
	v_lshl_add_u64 v[224:225], s[12:13], 0, v[128:129]
	s_mov_b32 m0, s21
	s_addc_u32 s77, s13, 0
	global_load_lds_dwordx4 v[224:225], off
	v_lshl_add_u64 v[240:241], s[76:77], 0, v[132:133]
	s_mov_b32 m0, s23
	v_lshl_add_u64 v[242:243], s[56:57], 0, v[130:131]
	global_load_lds_dwordx4 v[240:241], off
	v_lshl_add_u64 v[240:241], s[76:77], 0, v[128:129]
	s_mov_b32 m0, s33
	s_nop 0
	global_load_lds_dwordx4 v[240:241], off
	v_lshl_add_u64 v[240:241], s[56:57], 0, v[134:135]
	s_mov_b32 m0, s2
	s_nop 0
	global_load_lds_dwordx4 v[240:241], off
	s_mov_b32 m0, s36
	s_nop 0
	global_load_lds_dwordx4 v[242:243], off
	s_waitcnt vmcnt(16)
	s_cmp_lg_u32 s99, -1
	s_cbranch_scc1 .Lvmw_950_1
	s_waitcnt vmcnt(8)
; #define PG8_STAGE(bufoff, gbase, voff) do { _Pragma("unroll") for (int _i = 0; _i < 2; ++_i) \
;         __builtin_amdgcn_global_load_lds((const unsigned*)((const char*)(gbase) + (voff)[_i]), (PG8_LAS unsigned*)(lds + (bufoff) + ldsw + _i * 8192), 16, 0, 0); } while (0)
; #define PG8_LDA(dst, b, h) do { _Pragma("unroll") for (int m = 0; m < 4; ++m) _Pragma("unroll") for (int k = 0; k < 2; ++k) dst[m][k] = *(const PG8_LAS bf16x8*)(lds + PG8_SA(b, h) + aoff + m * 2048 + k * 1024); } while (0)
; #define PG8_LDB(dst, b, h) do { _Pragma("unroll") for (int n = 0; n < 2; ++n) _Pragma("unroll") for (int k = 0; k < 2; ++k) dst[n][k] = *(const PG8_LAS bf16x8*)(lds + PG8_SB(b, h) + boff + n * 2048 + k * 1024); } while (0)
; #define PG8_MMA(ai, bj, At, Bt) do { __builtin_amdgcn_s_setprio(1); _Pragma("unroll") for (int m = 0; m < 4; ++m) _Pragma("unroll") for (int n = 0; n < 2; ++n) _Pragma("unroll") for (int k = 0; k < 2; ++k) \
;         acc[ai][bj][m][n] = mma16<F16>(Bt[n][k], At[m][k], acc[ai][bj][m][n]); __builtin_amdgcn_s_setprio(0); } while (0)
; #define PG8_WAIT_V(n) asm volatile("s_waitcnt vmcnt(" #n ")" ::: "memory")
; #define PG8_WAIT_L(n) asm volatile("s_waitcnt lgkmcnt(" #n ")" ::: "memory")
; #define PG8_BAR __builtin_amdgcn_s_barrier()
; #define PG8_SCHED __builtin_amdgcn_sched_barrier(0)
; template <class Epi, class Sched, bool ALIGN_EPI = false, bool SP2 = false, bool F16 = false, bool TOKPERM = false>
; __device__ __forceinline__ void gemm_phase(PG8_LAS unsigned char* lds, const Gemm g, const Sched& S, const Epi& E, int wv) {
;     ...
;             PG8_WAIT_V(8); PG8_WAIT_L(0); PG8_BAR; PG8_MMA(1, 0, At, B0); PG8_MMA(1, 1, At, B1); PG8_BAR; PG8_SCHED;
;             PG8_LDB(B0, 1, 0); PG8_LDB(B1, 1, 1); PG8_SCHED; PG8_LDA(At, 1, 0); PG8_STAGE(PG8_SA(0, 1), a2 + hstep, voffA);
;             PG8_WAIT_V(8); PG8_WAIT_L(0); PG8_BAR; PG8_MMA(0, 0, At, B0); PG8_MMA(0, 1, At, B1); PG8_BAR; PG8_SCHED;
.Lvmw_950_1:
	s_waitcnt lgkmcnt(0)
	s_barrier
	s_setprio 1
	s_waitcnt lgkmcnt(0)
	v_mfma_f32_16x16x32_f16 v[60:63], v[172:175], v[204:207], 0
	v_mfma_f32_16x16x32_f16 v[56:59], v[180:183], v[204:207], 0
	v_mfma_f32_16x16x32_f16 v[44:47], v[172:175], v[212:215], 0
	v_mfma_f32_16x16x32_f16 v[40:43], v[180:183], v[212:215], 0
	v_mfma_f32_16x16x32_f16 v[28:31], v[172:175], v[220:223], 0
	v_mfma_f32_16x16x32_f16 v[24:27], v[180:183], v[220:223], 0
	v_mfma_f32_16x16x32_f16 v[12:15], v[172:175], v[232:235], 0
	v_mfma_f32_16x16x32_f16 v[8:11], v[180:183], v[232:235], 0
	v_mfma_f32_16x16x32_f16 v[60:63], v[176:179], v[208:211], v[60:63]
	v_mfma_f32_16x16x32_f16 v[56:59], v[184:187], v[208:211], v[56:59]
	v_mfma_f32_16x16x32_f16 v[44:47], v[176:179], v[216:219], v[44:47]
	v_mfma_f32_16x16x32_f16 v[40:43], v[184:187], v[216:219], v[40:43]
	v_mfma_f32_16x16x32_f16 v[28:31], v[176:179], v[228:231], v[28:31]
	v_mfma_f32_16x16x32_f16 v[24:27], v[184:187], v[228:231], v[24:27]
	v_mfma_f32_16x16x32_f16 v[12:15], v[176:179], v[236:239], v[12:15]
	v_mfma_f32_16x16x32_f16 v[8:11], v[184:187], v[236:239], v[8:11]
	s_setprio 0
	s_setprio 1
	v_mfma_f32_16x16x32_f16 v[52:55], v[188:191], v[204:207], 0
	v_mfma_f32_16x16x32_f16 v[48:51], v[196:199], v[204:207], 0
	v_mfma_f32_16x16x32_f16 v[36:39], v[188:191], v[212:215], 0
	v_mfma_f32_16x16x32_f16 v[32:35], v[196:199], v[212:215], 0
	v_mfma_f32_16x16x32_f16 v[20:23], v[188:191], v[220:223], 0
	v_mfma_f32_16x16x32_f16 v[16:19], v[196:199], v[220:223], 0
	v_mfma_f32_16x16x32_f16 v[4:7], v[188:191], v[232:235], 0
	v_mfma_f32_16x16x32_f16 v[0:3], v[196:199], v[232:235], 0
	v_mfma_f32_16x16x32_f16 v[52:55], v[192:195], v[208:211], v[52:55]
	v_mfma_f32_16x16x32_f16 v[48:51], v[200:203], v[208:211], v[48:51]
	v_mfma_f32_16x16x32_f16 v[36:39], v[192:195], v[216:219], v[36:39]
	v_mfma_f32_16x16x32_f16 v[32:35], v[200:203], v[216:219], v[32:35]
	v_mfma_f32_16x16x32_f16 v[20:23], v[192:195], v[228:231], v[20:23]
	v_mfma_f32_16x16x32_f16 v[16:19], v[200:203], v[228:231], v[16:19]
	v_mfma_f32_16x16x32_f16 v[4:7], v[192:195], v[236:239], v[4:7]
	v_mfma_f32_16x16x32_f16 v[0:3], v[200:203], v[236:239], v[0:3]
	s_setprio 0
	s_barrier
	ds_read_b128 v[172:175], v163
	ds_read_b128 v[176:179], v164
	ds_read_b128 v[180:183], v165
	ds_read_b128 v[184:187], v166
	ds_read_b128 v[188:191], v167
	ds_read_b128 v[192:195], v168
	ds_read_b128 v[196:199], v169
	ds_read_b128 v[200:203], v170
	s_add_u32 s56, s56, 0x40000
	s_addc_u32 s57, s57, 0
	s_mov_b32 m0, s37
	v_lshl_add_u64 v[244:245], s[56:57], 0, v[134:135]
	ds_read_b128 v[204:207], v153 offset:32768
	ds_read_b128 v[208:211], v153 offset:33792
	ds_read_b128 v[212:215], v153 offset:34816
	ds_read_b128 v[216:219], v153 offset:35840
	ds_read_b128 v[220:223], v153 offset:36864
	ds_read_b128 v[228:231], v153 offset:37888
	ds_read_b128 v[232:235], v153 offset:38912
	ds_read_b128 v[236:239], v153 offset:39936
	global_load_lds_dwordx4 v[244:245], off
	v_lshl_add_u64 v[244:245], s[56:57], 0, v[130:131]
	s_mov_b32 m0, s44
	s_nop 0
	global_load_lds_dwordx4 v[244:245], off
	s_waitcnt vmcnt(8)
	s_waitcnt lgkmcnt(0)
	s_barrier
	s_setprio 1
	s_waitcnt lgkmcnt(0)
	v_mfma_f32_16x16x32_f16 v[124:127], v[172:175], v[204:207], v[124:127]
	v_mfma_f32_16x16x32_f16 v[116:119], v[180:183], v[204:207], v[116:119]
	v_mfma_f32_16x16x32_f16 v[108:111], v[172:175], v[212:215], v[108:111]
	v_mfma_f32_16x16x32_f16 v[104:107], v[180:183], v[212:215], v[104:107]
	v_mfma_f32_16x16x32_f16 v[92:95], v[172:175], v[220:223], v[92:95]
	v_mfma_f32_16x16x32_f16 v[88:91], v[180:183], v[220:223], v[88:91]
	v_mfma_f32_16x16x32_f16 v[76:79], v[172:175], v[232:235], v[76:79]
	v_mfma_f32_16x16x32_f16 v[72:75], v[180:183], v[232:235], v[72:75]
	v_mfma_f32_16x16x32_f16 v[124:127], v[176:179], v[208:211], v[124:127]
	v_mfma_f32_16x16x32_f16 v[116:119], v[184:187], v[208:211], v[116:119]
	v_mfma_f32_16x16x32_f16 v[108:111], v[176:179], v[216:219], v[108:111]
	v_mfma_f32_16x16x32_f16 v[104:107], v[184:187], v[216:219], v[104:107]
	v_mfma_f32_16x16x32_f16 v[92:95], v[176:179], v[228:231], v[92:95]
	v_mfma_f32_16x16x32_f16 v[88:91], v[184:187], v[228:231], v[88:91]
	v_mfma_f32_16x16x32_f16 v[76:79], v[176:179], v[236:239], v[76:79]
	v_mfma_f32_16x16x32_f16 v[72:75], v[184:187], v[236:239], v[72:75]
	s_setprio 0
	s_setprio 1
	v_mfma_f32_16x16x32_f16 v[120:123], v[188:191], v[204:207], v[120:123]
	v_mfma_f32_16x16x32_f16 v[112:115], v[196:199], v[204:207], v[112:115]
	v_mfma_f32_16x16x32_f16 v[100:103], v[188:191], v[212:215], v[100:103]
	v_mfma_f32_16x16x32_f16 v[96:99], v[196:199], v[212:215], v[96:99]
	v_mfma_f32_16x16x32_f16 v[84:87], v[188:191], v[220:223], v[84:87]
	v_mfma_f32_16x16x32_f16 v[80:83], v[196:199], v[220:223], v[80:83]
	v_mfma_f32_16x16x32_f16 v[68:71], v[188:191], v[232:235], v[68:71]
	v_mfma_f32_16x16x32_f16 v[64:67], v[196:199], v[232:235], v[64:67]
	v_mfma_f32_16x16x32_f16 v[120:123], v[192:195], v[208:211], v[120:123]
	v_mfma_f32_16x16x32_f16 v[112:115], v[200:203], v[208:211], v[112:115]
	v_mfma_f32_16x16x32_f16 v[100:103], v[192:195], v[216:219], v[100:103]
	v_mfma_f32_16x16x32_f16 v[96:99], v[200:203], v[216:219], v[96:99]
	v_mfma_f32_16x16x32_f16 v[84:87], v[192:195], v[228:231], v[84:87]
	v_mfma_f32_16x16x32_f16 v[80:83], v[200:203], v[228:231], v[80:83]
	v_mfma_f32_16x16x32_f16 v[68:71], v[192:195], v[236:239], v[68:71]
	v_mfma_f32_16x16x32_f16 v[64:67], v[200:203], v[236:239], v[64:67]
	s_setprio 0
	s_barrier
; #define PG8_STAGE(bufoff, gbase, voff) do { _Pragma("unroll") for (int _i = 0; _i < 2; ++_i) \
;         __builtin_amdgcn_global_load_lds((const unsigned*)((const char*)(gbase) + (voff)[_i]), (PG8_LAS unsigned*)(lds + (bufoff) + ldsw + _i * 8192), 16, 0, 0); } while (0)
; #define PG8_LDA(dst, b, h) do { _Pragma("unroll") for (int m = 0; m < 4; ++m) _Pragma("unroll") for (int k = 0; k < 2; ++k) dst[m][k] = *(const PG8_LAS bf16x8*)(lds + PG8_SA(b, h) + aoff + m * 2048 + k * 1024); } while (0)
; #define PG8_MMA(ai, bj, At, Bt) do { __builtin_amdgcn_s_setprio(1); _Pragma("unroll") for (int m = 0; m < 4; ++m) _Pragma("unroll") for (int n = 0; n < 2; ++n) _Pragma("unroll") for (int k = 0; k < 2; ++k) \
;         acc[ai][bj][m][n] = mma16<F16>(Bt[n][k], At[m][k], acc[ai][bj][m][n]); __builtin_amdgcn_s_setprio(0); } while (0)
; #define PG8_WAIT_V(n) asm volatile("s_waitcnt vmcnt(" #n ")" ::: "memory")
; #define PG8_WAIT_L(n) asm volatile("s_waitcnt lgkmcnt(" #n ")" ::: "memory")
; #define PG8_BAR __builtin_amdgcn_s_barrier()
; #define PG8_SCHED __builtin_amdgcn_sched_barrier(0)
; template <class Epi, class Sched, bool ALIGN_EPI = false, bool SP2 = false, bool F16 = false, bool TOKPERM = false>
; __device__ __forceinline__ void gemm_phase(PG8_LAS unsigned char* lds, const Gemm g, const Sched& S, const Epi& E, int wv) {
;     ...
;             PG8_LDA(At, 1, 1); PG8_STAGE(PG8_SB(1, 0), b3, voffB); PG8_STAGE(PG8_SB(1, 1), b3 + hstep, voffB); PG8_STAGE(PG8_SA(1, 0), a3, voffA);
;             PG8_WAIT_V(8); PG8_WAIT_L(0); PG8_BAR; PG8_MMA(1, 0, At, B0); PG8_MMA(1, 1, At, B1); PG8_BAR; PG8_SCHED;
	s_mov_b32 m0, s58
	v_lshl_add_u64 v[148:149], v[148:149], 0, s[16:17]
	s_add_u32 s12, s12, 0x40080
	ds_read_b128 v[204:207], v153 offset:49152
	ds_read_b128 v[208:211], v153 offset:50176
	ds_read_b128 v[212:215], v153 offset:51200
	ds_read_b128 v[216:219], v153 offset:52224
	ds_read_b128 v[220:223], v153 offset:53248
	ds_read_b128 v[228:231], v153 offset:54272
	ds_read_b128 v[232:235], v153 offset:55296
	ds_read_b128 v[236:239], v153 offset:56320
	global_load_lds_dwordx4 v[148:149], off
	v_lshl_add_u64 v[148:149], v[224:225], 0, s[16:17]
	s_mov_b32 m0, s59
	s_addc_u32 s13, s13, 0
	global_load_lds_dwordx4 v[148:149], off
	v_lshl_add_u64 v[148:149], s[12:13], 0, v[132:133]
	s_mov_b32 m0, s62
	s_nop 0
	global_load_lds_dwordx4 v[148:149], off
	v_lshl_add_u64 v[148:149], s[12:13], 0, v[128:129]
	s_mov_b32 m0, s63
	s_nop 0
	global_load_lds_dwordx4 v[148:149], off
	v_lshl_add_u64 v[148:149], v[240:241], 0, s[16:17]
	s_mov_b32 m0, s60
	s_nop 0
	global_load_lds_dwordx4 v[148:149], off
	v_lshl_add_u64 v[148:149], v[242:243], 0, s[16:17]
	s_mov_b32 m0, s61
	s_nop 0
	global_load_lds_dwordx4 v[148:149], off
	s_waitcnt vmcnt(8)
	s_waitcnt lgkmcnt(0)
	s_barrier
	s_setprio 1
	s_waitcnt lgkmcnt(0)
	v_mfma_f32_16x16x32_f16 v[60:63], v[172:175], v[204:207], v[60:63]
	v_mfma_f32_16x16x32_f16 v[56:59], v[180:183], v[204:207], v[56:59]
	v_mfma_f32_16x16x32_f16 v[44:47], v[172:175], v[212:215], v[44:47]
	v_mfma_f32_16x16x32_f16 v[40:43], v[180:183], v[212:215], v[40:43]
	v_mfma_f32_16x16x32_f16 v[28:31], v[172:175], v[220:223], v[28:31]
	v_mfma_f32_16x16x32_f16 v[24:27], v[180:183], v[220:223], v[24:27]
	v_mfma_f32_16x16x32_f16 v[12:15], v[172:175], v[232:235], v[12:15]
	v_mfma_f32_16x16x32_f16 v[8:11], v[180:183], v[232:235], v[8:11]
	v_mfma_f32_16x16x32_f16 v[60:63], v[176:179], v[208:211], v[60:63]
	v_mfma_f32_16x16x32_f16 v[56:59], v[184:187], v[208:211], v[56:59]
	v_mfma_f32_16x16x32_f16 v[44:47], v[176:179], v[216:219], v[44:47]
	v_mfma_f32_16x16x32_f16 v[40:43], v[184:187], v[216:219], v[40:43]
	v_mfma_f32_16x16x32_f16 v[28:31], v[176:179], v[228:231], v[28:31]
	v_mfma_f32_16x16x32_f16 v[24:27], v[184:187], v[228:231], v[24:27]
	v_mfma_f32_16x16x32_f16 v[12:15], v[176:179], v[236:239], v[12:15]
	v_mfma_f32_16x16x32_f16 v[8:11], v[184:187], v[236:239], v[8:11]
	s_setprio 0
	s_setprio 1
	v_mfma_f32_16x16x32_f16 v[52:55], v[188:191], v[204:207], v[52:55]
	v_mfma_f32_16x16x32_f16 v[48:51], v[196:199], v[204:207], v[48:51]
	v_mfma_f32_16x16x32_f16 v[36:39], v[188:191], v[212:215], v[36:39]
	v_mfma_f32_16x16x32_f16 v[32:35], v[196:199], v[212:215], v[32:35]
	v_mfma_f32_16x16x32_f16 v[20:23], v[188:191], v[220:223], v[20:23]
	v_mfma_f32_16x16x32_f16 v[16:19], v[196:199], v[220:223], v[16:19]
	v_mfma_f32_16x16x32_f16 v[4:7], v[188:191], v[232:235], v[4:7]
	v_mfma_f32_16x16x32_f16 v[0:3], v[196:199], v[232:235], v[0:3]
	v_mfma_f32_16x16x32_f16 v[52:55], v[192:195], v[208:211], v[52:55]
	v_mfma_f32_16x16x32_f16 v[48:51], v[200:203], v[208:211], v[48:51]
	v_mfma_f32_16x16x32_f16 v[36:39], v[192:195], v[216:219], v[36:39]
	v_mfma_f32_16x16x32_f16 v[32:35], v[200:203], v[216:219], v[32:35]
	v_mfma_f32_16x16x32_f16 v[20:23], v[192:195], v[228:231], v[20:23]
	v_mfma_f32_16x16x32_f16 v[16:19], v[200:203], v[228:231], v[16:19]
	v_mfma_f32_16x16x32_f16 v[4:7], v[192:195], v[236:239], v[4:7]
	v_mfma_f32_16x16x32_f16 v[0:3], v[200:203], v[236:239], v[0:3]
	s_setprio 0
	s_barrier
	s_add_i32 s74, s74, 2
	s_add_u32 s10, s10, 0x100
	s_addc_u32 s11, s11, 0
	s_add_u32 s72, s72, 0x100
	s_addc_u32 s73, s73, 0
	s_cmp_gt_u32 s74, 13

; #define PG8_STAGE(bufoff, gbase, voff) do { _Pragma("unroll") for (int _i = 0; _i < 2; ++_i) \
;         __builtin_amdgcn_global_load_lds((const unsigned*)((const char*)(gbase) + (voff)[_i]), (PG8_LAS unsigned*)(lds + (bufoff) + ldsw + _i * 8192), 16, 0, 0); } while (0)
; #define PG8_LDA(dst, b, h) do { _Pragma("unroll") for (int m = 0; m < 4; ++m) _Pragma("unroll") for (int k = 0; k < 2; ++k) dst[m][k] = *(const PG8_LAS bf16x8*)(lds + PG8_SA(b, h) + aoff + m * 2048 + k * 1024); } while (0)
; #define PG8_LDB(dst, b, h) do { _Pragma("unroll") for (int n = 0; n < 2; ++n) _Pragma("unroll") for (int k = 0; k < 2; ++k) dst[n][k] = *(const PG8_LAS bf16x8*)(lds + PG8_SB(b, h) + boff + n * 2048 + k * 1024); } while (0)
; #define PG8_MMA(ai, bj, At, Bt) do { __builtin_amdgcn_s_setprio(1); _Pragma("unroll") for (int m = 0; m < 4; ++m) _Pragma("unroll") for (int n = 0; n < 2; ++n) _Pragma("unroll") for (int k = 0; k < 2; ++k) \
;         acc[ai][bj][m][n] = mma16<F16>(Bt[n][k], At[m][k], acc[ai][bj][m][n]); __builtin_amdgcn_s_setprio(0); } while (0)
; #define PG8_WAIT_V(n) asm volatile("s_waitcnt vmcnt(" #n ")" ::: "memory")
; #define PG8_WAIT_L(n) asm volatile("s_waitcnt lgkmcnt(" #n ")" ::: "memory")
; template <class Epi, class Sched, bool ALIGN_EPI = false, bool SP2 = false, bool F16 = false, bool TOKPERM = false>
; __device__ __forceinline__ void gemm_phase(PG8_LAS unsigned char* lds, const Gemm g, const Sched& S, const Epi& E, int wv) {
;     ...
;         const bool has_next = S.next(ui + 1, nxt);
;         const char* nA = has_next ? (const char*)g.A + (size_t)nxt.pm * tstep : cA; const char* nB = has_next ? (const char*)g.Bt + (size_t)nxt.pn * tstep : cB;
;         for (int t = 0; t < nt; t += 2) {
;             const bool last = (t == nt - 2);
;             const char* a1 = cA + (size_t)(t + 1) * kstep;
;             const char* a2 = last ? nA : cA + (size_t)(t + 2) * kstep; const char* b2 = last ? nB : cB + (size_t)(t + 2) * kstep;
;             const char* a3 = a2 + kstep; const char* b3 = b2 + kstep;
;             if (last && has_next) S.a_ready(nxt);
;             if constexpr (SP2) {
;             PG8_LDB(B0, 0, 0); PG8_LDB(B1, 0, 1); PG8_SCHED; PG8_LDA(At, 0, 0); PG8_STAGE(PG8_SA(1, 1), a1 + hstep, voffA);
;             PG8_WAIT_V(8); PG8_WAIT_L(0); PG8_BAR; PG8_MMA(0, 0, At, B0); PG8_MMA(0, 1, At, B1); PG8_BAR; PG8_SCHED;
.LBB0_1606:
	s_ashr_i32 s25, s24, 31
	s_lshl_b64 s[36:37], s[24:25], 19
	s_add_u32 s36, s40, s36
	s_addc_u32 s37, s41, s37
	s_and_b64 s[42:43], s[4:5], exec
	s_cselect_b32 s25, s37, s9
	s_cselect_b32 s64, s36, s8
	s_ashr_i32 s23, s22, 31
	s_lshl_b64 s[42:43], s[22:23], 19
	s_add_u32 s42, s0, s42
	s_addc_u32 s43, s1, s43
	s_and_b64 s[44:45], s[4:5], exec
	s_cselect_b32 s23, s43, s11
	s_cselect_b32 s65, s42, s10
	s_add_u32 s8, s8, 0x40080
	s_addc_u32 s9, s9, 0
	s_add_u32 s66, s10, 0x100
	s_addc_u32 s67, s11, 0
	s_mov_b32 s68, -2
	ds_read_b128 v[172:175], v155
	ds_read_b128 v[176:179], v156
	ds_read_b128 v[180:183], v157
	ds_read_b128 v[184:187], v158
	ds_read_b128 v[188:191], v159
	ds_read_b128 v[192:195], v160
	ds_read_b128 v[196:199], v161
	ds_read_b128 v[200:203], v162
	s_add_u32 s10, s8, 0xfffc0080
	s_addc_u32 s11, s9, -1
	s_cmp_eq_u32 s68, 12
	s_cselect_b32 s45, s25, s11
	s_cselect_b32 s44, s64, s10
	s_cselect_b32 s11, s23, s67
	s_cselect_b32 s10, s65, s66
	s_mov_b32 m0, s60
	v_lshl_add_u64 v[148:149], s[8:9], 0, v[140:141]
	ds_read_b128 v[204:207], v153
	ds_read_b128 v[208:211], v153 offset:1024
	ds_read_b128 v[212:215], v153 offset:2048
	ds_read_b128 v[216:219], v153 offset:3072
	ds_read_b128 v[220:223], v153 offset:4096
	ds_read_b128 v[224:227], v153 offset:5120
	ds_read_b128 v[228:231], v153 offset:6144
	ds_read_b128 v[232:235], v153 offset:7168
	global_load_lds_dwordx4 v[148:149], off
	v_lshl_add_u64 v[148:149], s[8:9], 0, v[142:143]
	s_mov_b32 m0, s61
	s_nop 0
	global_load_lds_dwordx4 v[148:149], off
	s_waitcnt vmcnt(16)
	s_cmp_lg_u32 s99, -1
	s_cbranch_scc1 .Lvmw_1607_0
	s_waitcnt vmcnt(8)
.Lvmw_1607_0:
	s_waitcnt lgkmcnt(0)
	s_barrier
	s_setprio 1
	s_waitcnt lgkmcnt(0)
	v_mfma_f32_16x16x32_f16 v[124:127], v[172:175], v[204:207], 0
	v_mfma_f32_16x16x32_f16 v[116:119], v[180:183], v[204:207], 0
	v_mfma_f32_16x16x32_f16 v[108:111], v[172:175], v[212:215], 0
	v_mfma_f32_16x16x32_f16 v[104:107], v[180:183], v[212:215], 0
	v_mfma_f32_16x16x32_f16 v[92:95], v[172:175], v[220:223], 0
	v_mfma_f32_16x16x32_f16 v[88:91], v[180:183], v[220:223], 0
	v_mfma_f32_16x16x32_f16 v[76:79], v[172:175], v[228:231], 0
	v_mfma_f32_16x16x32_f16 v[72:75], v[180:183], v[228:231], 0
	v_mfma_f32_16x16x32_f16 v[124:127], v[176:179], v[208:211], v[124:127]
	v_mfma_f32_16x16x32_f16 v[116:119], v[184:187], v[208:211], v[116:119]
	v_mfma_f32_16x16x32_f16 v[108:111], v[176:179], v[216:219], v[108:111]
	v_mfma_f32_16x16x32_f16 v[104:107], v[184:187], v[216:219], v[104:107]
	v_mfma_f32_16x16x32_f16 v[92:95], v[176:179], v[224:227], v[92:95]
	v_mfma_f32_16x16x32_f16 v[88:91], v[184:187], v[224:227], v[88:91]
	v_mfma_f32_16x16x32_f16 v[76:79], v[176:179], v[232:235], v[76:79]
	v_mfma_f32_16x16x32_f16 v[72:75], v[184:187], v[232:235], v[72:75]
	s_setprio 0
	s_setprio 1
	v_mfma_f32_16x16x32_f16 v[120:123], v[188:191], v[204:207], 0
	v_mfma_f32_16x16x32_f16 v[112:115], v[196:199], v[204:207], 0
	v_mfma_f32_16x16x32_f16 v[100:103], v[188:191], v[212:215], 0
	v_mfma_f32_16x16x32_f16 v[96:99], v[196:199], v[212:215], 0
	v_mfma_f32_16x16x32_f16 v[84:87], v[188:191], v[220:223], 0
	v_mfma_f32_16x16x32_f16 v[80:83], v[196:199], v[220:223], 0
	v_mfma_f32_16x16x32_f16 v[68:71], v[188:191], v[228:231], 0
	v_mfma_f32_16x16x32_f16 v[64:67], v[196:199], v[228:231], 0
	v_mfma_f32_16x16x32_f16 v[120:123], v[192:195], v[208:211], v[120:123]
	v_mfma_f32_16x16x32_f16 v[112:115], v[200:203], v[208:211], v[112:115]
	v_mfma_f32_16x16x32_f16 v[100:103], v[192:195], v[216:219], v[100:103]
	v_mfma_f32_16x16x32_f16 v[96:99], v[200:203], v[216:219], v[96:99]
	v_mfma_f32_16x16x32_f16 v[84:87], v[192:195], v[224:227], v[84:87]
	v_mfma_f32_16x16x32_f16 v[80:83], v[200:203], v[224:227], v[80:83]
	v_mfma_f32_16x16x32_f16 v[68:71], v[192:195], v[232:235], v[68:71]
	v_mfma_f32_16x16x32_f16 v[64:67], v[200:203], v[232:235], v[64:67]
	s_setprio 0
	s_barrier
	s_mov_b32 m0, s21
	v_lshl_add_u64 v[148:149], s[10:11], 0, v[132:133]
	s_add_u32 s70, s10, 0x40000
	ds_read_b128 v[204:207], v153 offset:16384
	ds_read_b128 v[208:211], v153 offset:17408
	ds_read_b128 v[212:215], v153 offset:18432
	ds_read_b128 v[216:219], v153 offset:19456
	ds_read_b128 v[220:223], v153 offset:20480
	ds_read_b128 v[224:227], v153 offset:21504
	ds_read_b128 v[228:231], v153 offset:22528
	ds_read_b128 v[232:235], v153 offset:23552
	global_load_lds_dwordx4 v[148:149], off
	v_lshl_add_u64 v[236:237], s[10:11], 0, v[128:129]
	s_mov_b32 m0, s33
	s_addc_u32 s71, s11, 0
	global_load_lds_dwordx4 v[236:237], off
	v_lshl_add_u64 v[238:239], s[70:71], 0, v[132:133]
	s_mov_b32 m0, s46
	v_lshl_add_u64 v[240:241], s[44:45], 0, v[130:131]
	global_load_lds_dwordx4 v[238:239], off
	v_lshl_add_u64 v[238:239], s[70:71], 0, v[128:129]
	s_mov_b32 m0, s47
	s_nop 0
	global_load_lds_dwordx4 v[238:239], off
	v_lshl_add_u64 v[238:239], s[44:45], 0, v[134:135]
	s_mov_b32 m0, s2
	s_nop 0
	global_load_lds_dwordx4 v[238:239], off
	s_mov_b32 m0, s48
	s_nop 0
	global_load_lds_dwordx4 v[240:241], off
	s_waitcnt vmcnt(16)
	s_cmp_lg_u32 s99, -1
	s_cbranch_scc1 .Lvmw_1607_1
	s_waitcnt vmcnt(8)
; #define PG8_STAGE(bufoff, gbase, voff) do { _Pragma("unroll") for (int _i = 0; _i < 2; ++_i) \
;         __builtin_amdgcn_global_load_lds((const unsigned*)((const char*)(gbase) + (voff)[_i]), (PG8_LAS unsigned*)(lds + (bufoff) + ldsw + _i * 8192), 16, 0, 0); } while (0)
; #define PG8_LDA(dst, b, h) do { _Pragma("unroll") for (int m = 0; m < 4; ++m) _Pragma("unroll") for (int k = 0; k < 2; ++k) dst[m][k] = *(const PG8_LAS bf16x8*)(lds + PG8_SA(b, h) + aoff + m * 2048 + k * 1024); } while (0)
; #define PG8_LDB(dst, b, h) do { _Pragma("unroll") for (int n = 0; n < 2; ++n) _Pragma("unroll") for (int k = 0; k < 2; ++k) dst[n][k] = *(const PG8_LAS bf16x8*)(lds + PG8_SB(b, h) + boff + n * 2048 + k * 1024); } while (0)
; #define PG8_MMA(ai, bj, At, Bt) do { __builtin_amdgcn_s_setprio(1); _Pragma("unroll") for (int m = 0; m < 4; ++m) _Pragma("unroll") for (int n = 0; n < 2; ++n) _Pragma("unroll") for (int k = 0; k < 2; ++k) \
;         acc[ai][bj][m][n] = mma16<F16>(Bt[n][k], At[m][k], acc[ai][bj][m][n]); __builtin_amdgcn_s_setprio(0); } while (0)
; #define PG8_WAIT_V(n) asm volatile("s_waitcnt vmcnt(" #n ")" ::: "memory")
; #define PG8_WAIT_L(n) asm volatile("s_waitcnt lgkmcnt(" #n ")" ::: "memory")
; #define PG8_BAR __builtin_amdgcn_s_barrier()
; #define PG8_SCHED __builtin_amdgcn_sched_barrier(0)
; template <class Epi, class Sched, bool ALIGN_EPI = false, bool SP2 = false, bool F16 = false, bool TOKPERM = false>
; __device__ __forceinline__ void gemm_phase(PG8_LAS unsigned char* lds, const Gemm g, const Sched& S, const Epi& E, int wv) {
;     ...
;             PG8_LDA(At, 0, 1); PG8_STAGE(PG8_SB(0, 0), b2, voffB); PG8_STAGE(PG8_SB(0, 1), b2 + hstep, voffB); PG8_STAGE(PG8_SA(0, 0), a2, voffA);
;             PG8_WAIT_V(8); PG8_WAIT_L(0); PG8_BAR; PG8_MMA(1, 0, At, B0); PG8_MMA(1, 1, At, B1); PG8_BAR; PG8_SCHED;
;             PG8_LDB(B0, 1, 0); PG8_LDB(B1, 1, 1); PG8_SCHED; PG8_LDA(At, 1, 0); PG8_STAGE(PG8_SA(0, 1), a2 + hstep, voffA);
;             PG8_WAIT_V(8); PG8_WAIT_L(0); PG8_BAR; PG8_MMA(0, 0, At, B0); PG8_MMA(0, 1, At, B1); PG8_BAR; PG8_SCHED;
.Lvmw_1607_1:
	s_waitcnt lgkmcnt(0)
	s_barrier
	s_setprio 1
	s_waitcnt lgkmcnt(0)
	v_mfma_f32_16x16x32_f16 v[60:63], v[172:175], v[204:207], 0
	v_mfma_f32_16x16x32_f16 v[56:59], v[180:183], v[204:207], 0
	v_mfma_f32_16x16x32_f16 v[44:47], v[172:175], v[212:215], 0
	v_mfma_f32_16x16x32_f16 v[40:43], v[180:183], v[212:215], 0
	v_mfma_f32_16x16x32_f16 v[28:31], v[172:175], v[220:223], 0
	v_mfma_f32_16x16x32_f16 v[24:27], v[180:183], v[220:223], 0
	v_mfma_f32_16x16x32_f16 v[12:15], v[172:175], v[228:231], 0
	v_mfma_f32_16x16x32_f16 v[8:11], v[180:183], v[228:231], 0
	v_mfma_f32_16x16x32_f16 v[60:63], v[176:179], v[208:211], v[60:63]
	v_mfma_f32_16x16x32_f16 v[56:59], v[184:187], v[208:211], v[56:59]
	v_mfma_f32_16x16x32_f16 v[44:47], v[176:179], v[216:219], v[44:47]
	v_mfma_f32_16x16x32_f16 v[40:43], v[184:187], v[216:219], v[40:43]
	v_mfma_f32_16x16x32_f16 v[28:31], v[176:179], v[224:227], v[28:31]
	v_mfma_f32_16x16x32_f16 v[24:27], v[184:187], v[224:227], v[24:27]
	v_mfma_f32_16x16x32_f16 v[12:15], v[176:179], v[232:235], v[12:15]
	v_mfma_f32_16x16x32_f16 v[8:11], v[184:187], v[232:235], v[8:11]
	s_setprio 0
	s_setprio 1
	v_mfma_f32_16x16x32_f16 v[52:55], v[188:191], v[204:207], 0
	v_mfma_f32_16x16x32_f16 v[48:51], v[196:199], v[204:207], 0
	v_mfma_f32_16x16x32_f16 v[36:39], v[188:191], v[212:215], 0
	v_mfma_f32_16x16x32_f16 v[32:35], v[196:199], v[212:215], 0
	v_mfma_f32_16x16x32_f16 v[20:23], v[188:191], v[220:223], 0
	v_mfma_f32_16x16x32_f16 v[16:19], v[196:199], v[220:223], 0
	v_mfma_f32_16x16x32_f16 v[4:7], v[188:191], v[228:231], 0
	v_mfma_f32_16x16x32_f16 v[0:3], v[196:199], v[228:231], 0
	v_mfma_f32_16x16x32_f16 v[52:55], v[192:195], v[208:211], v[52:55]
	v_mfma_f32_16x16x32_f16 v[48:51], v[200:203], v[208:211], v[48:51]
	v_mfma_f32_16x16x32_f16 v[36:39], v[192:195], v[216:219], v[36:39]
	v_mfma_f32_16x16x32_f16 v[32:35], v[200:203], v[216:219], v[32:35]
	v_mfma_f32_16x16x32_f16 v[20:23], v[192:195], v[224:227], v[20:23]
	v_mfma_f32_16x16x32_f16 v[16:19], v[200:203], v[224:227], v[16:19]
	v_mfma_f32_16x16x32_f16 v[4:7], v[192:195], v[232:235], v[4:7]
	v_mfma_f32_16x16x32_f16 v[0:3], v[200:203], v[232:235], v[0:3]
	s_setprio 0
	s_barrier
	ds_read_b128 v[172:175], v163
	ds_read_b128 v[176:179], v164
	ds_read_b128 v[180:183], v165
	ds_read_b128 v[184:187], v166
	ds_read_b128 v[188:191], v167
	ds_read_b128 v[192:195], v168
	ds_read_b128 v[196:199], v169
	ds_read_b128 v[200:203], v170
	s_add_u32 s44, s44, 0x40000
	s_addc_u32 s45, s45, 0
	s_mov_b32 m0, s49
	v_lshl_add_u64 v[242:243], s[44:45], 0, v[134:135]
	ds_read_b128 v[204:207], v153 offset:32768
	ds_read_b128 v[208:211], v153 offset:33792
	ds_read_b128 v[212:215], v153 offset:34816
	ds_read_b128 v[216:219], v153 offset:35840
	ds_read_b128 v[220:223], v153 offset:36864
	ds_read_b128 v[224:227], v153 offset:37888
	ds_read_b128 v[228:231], v153 offset:38912
	ds_read_b128 v[232:235], v153 offset:39936
	global_load_lds_dwordx4 v[242:243], off
	v_lshl_add_u64 v[242:243], s[44:45], 0, v[130:131]
	s_mov_b32 m0, s50
	s_nop 0
	global_load_lds_dwordx4 v[242:243], off
	s_waitcnt vmcnt(8)
	s_waitcnt lgkmcnt(0)
	s_barrier
	s_setprio 1
	s_waitcnt lgkmcnt(0)
	v_mfma_f32_16x16x32_f16 v[124:127], v[172:175], v[204:207], v[124:127]
	v_mfma_f32_16x16x32_f16 v[116:119], v[180:183], v[204:207], v[116:119]
	v_mfma_f32_16x16x32_f16 v[108:111], v[172:175], v[212:215], v[108:111]
	v_mfma_f32_16x16x32_f16 v[104:107], v[180:183], v[212:215], v[104:107]
	v_mfma_f32_16x16x32_f16 v[92:95], v[172:175], v[220:223], v[92:95]
	v_mfma_f32_16x16x32_f16 v[88:91], v[180:183], v[220:223], v[88:91]
	v_mfma_f32_16x16x32_f16 v[76:79], v[172:175], v[228:231], v[76:79]
	v_mfma_f32_16x16x32_f16 v[72:75], v[180:183], v[228:231], v[72:75]
	v_mfma_f32_16x16x32_f16 v[124:127], v[176:179], v[208:211], v[124:127]
	v_mfma_f32_16x16x32_f16 v[116:119], v[184:187], v[208:211], v[116:119]
	v_mfma_f32_16x16x32_f16 v[108:111], v[176:179], v[216:219], v[108:111]
	v_mfma_f32_16x16x32_f16 v[104:107], v[184:187], v[216:219], v[104:107]
	v_mfma_f32_16x16x32_f16 v[92:95], v[176:179], v[224:227], v[92:95]
	v_mfma_f32_16x16x32_f16 v[88:91], v[184:187], v[224:227], v[88:91]
	v_mfma_f32_16x16x32_f16 v[76:79], v[176:179], v[232:235], v[76:79]
	v_mfma_f32_16x16x32_f16 v[72:75], v[184:187], v[232:235], v[72:75]
	s_setprio 0
	s_setprio 1
	v_mfma_f32_16x16x32_f16 v[120:123], v[188:191], v[204:207], v[120:123]
	v_mfma_f32_16x16x32_f16 v[112:115], v[196:199], v[204:207], v[112:115]
	v_mfma_f32_16x16x32_f16 v[100:103], v[188:191], v[212:215], v[100:103]
	v_mfma_f32_16x16x32_f16 v[96:99], v[196:199], v[212:215], v[96:99]
	v_mfma_f32_16x16x32_f16 v[84:87], v[188:191], v[220:223], v[84:87]
	v_mfma_f32_16x16x32_f16 v[80:83], v[196:199], v[220:223], v[80:83]
	v_mfma_f32_16x16x32_f16 v[68:71], v[188:191], v[228:231], v[68:71]
	v_mfma_f32_16x16x32_f16 v[64:67], v[196:199], v[228:231], v[64:67]
	v_mfma_f32_16x16x32_f16 v[120:123], v[192:195], v[208:211], v[120:123]
	v_mfma_f32_16x16x32_f16 v[112:115], v[200:203], v[208:211], v[112:115]
	v_mfma_f32_16x16x32_f16 v[100:103], v[192:195], v[216:219], v[100:103]
	v_mfma_f32_16x16x32_f16 v[96:99], v[200:203], v[216:219], v[96:99]
	v_mfma_f32_16x16x32_f16 v[84:87], v[192:195], v[224:227], v[84:87]
	v_mfma_f32_16x16x32_f16 v[80:83], v[200:203], v[224:227], v[80:83]
	v_mfma_f32_16x16x32_f16 v[68:71], v[192:195], v[232:235], v[68:71]
	v_mfma_f32_16x16x32_f16 v[64:67], v[200:203], v[232:235], v[64:67]
	s_setprio 0
	s_barrier
; #define PG8_STAGE(bufoff, gbase, voff) do { _Pragma("unroll") for (int _i = 0; _i < 2; ++_i) \
;         __builtin_amdgcn_global_load_lds((const unsigned*)((const char*)(gbase) + (voff)[_i]), (PG8_LAS unsigned*)(lds + (bufoff) + ldsw + _i * 8192), 16, 0, 0); } while (0)
; #define PG8_LDA(dst, b, h) do { _Pragma("unroll") for (int m = 0; m < 4; ++m) _Pragma("unroll") for (int k = 0; k < 2; ++k) dst[m][k] = *(const PG8_LAS bf16x8*)(lds + PG8_SA(b, h) + aoff + m * 2048 + k * 1024); } while (0)
; #define PG8_MMA(ai, bj, At, Bt) do { __builtin_amdgcn_s_setprio(1); _Pragma("unroll") for (int m = 0; m < 4; ++m) _Pragma("unroll") for (int n = 0; n < 2; ++n) _Pragma("unroll") for (int k = 0; k < 2; ++k) \
;         acc[ai][bj][m][n] = mma16<F16>(Bt[n][k], At[m][k], acc[ai][bj][m][n]); __builtin_amdgcn_s_setprio(0); } while (0)
; #define PG8_WAIT_V(n) asm volatile("s_waitcnt vmcnt(" #n ")" ::: "memory")
; #define PG8_WAIT_L(n) asm volatile("s_waitcnt lgkmcnt(" #n ")" ::: "memory")
; #define PG8_BAR __builtin_amdgcn_s_barrier()
; #define PG8_SCHED __builtin_amdgcn_sched_barrier(0)
; template <class Epi, class Sched, bool ALIGN_EPI = false, bool SP2 = false, bool F16 = false, bool TOKPERM = false>
; __device__ __forceinline__ void gemm_phase(PG8_LAS unsigned char* lds, const Gemm g, const Sched& S, const Epi& E, int wv) {
;     ...
;             PG8_LDA(At, 1, 1); PG8_STAGE(PG8_SB(1, 0), b3, voffB); PG8_STAGE(PG8_SB(1, 1), b3 + hstep, voffB); PG8_STAGE(PG8_SA(1, 0), a3, voffA);
;             PG8_WAIT_V(8); PG8_WAIT_L(0); PG8_BAR; PG8_MMA(1, 0, At, B0); PG8_MMA(1, 1, At, B1); PG8_BAR; PG8_SCHED;
	s_mov_b32 m0, s52
	v_lshl_add_u64 v[148:149], v[148:149], 0, s[14:15]
	s_add_u32 s10, s10, 0x40080
	ds_read_b128 v[204:207], v153 offset:49152
	ds_read_b128 v[208:211], v153 offset:50176
	ds_read_b128 v[212:215], v153 offset:51200
	ds_read_b128 v[216:219], v153 offset:52224
	ds_read_b128 v[220:223], v153 offset:53248
	ds_read_b128 v[224:227], v153 offset:54272
	ds_read_b128 v[228:231], v153 offset:55296
	ds_read_b128 v[232:235], v153 offset:56320
	global_load_lds_dwordx4 v[148:149], off
	v_lshl_add_u64 v[148:149], v[236:237], 0, s[14:15]
	s_mov_b32 m0, s53
	s_addc_u32 s11, s11, 0
	global_load_lds_dwordx4 v[148:149], off
	v_lshl_add_u64 v[148:149], s[10:11], 0, v[132:133]
	s_mov_b32 m0, s56
	s_nop 0
	global_load_lds_dwordx4 v[148:149], off
	v_lshl_add_u64 v[148:149], s[10:11], 0, v[128:129]
	s_mov_b32 m0, s57
	s_nop 0
	global_load_lds_dwordx4 v[148:149], off
	v_lshl_add_u64 v[148:149], v[238:239], 0, s[14:15]
	s_mov_b32 m0, s54
	s_nop 0
	global_load_lds_dwordx4 v[148:149], off
	v_lshl_add_u64 v[148:149], v[240:241], 0, s[14:15]
	s_mov_b32 m0, s55
	s_nop 0
	global_load_lds_dwordx4 v[148:149], off
	s_waitcnt vmcnt(8)
	s_waitcnt lgkmcnt(0)
	s_barrier
	s_setprio 1
	s_waitcnt lgkmcnt(0)
	v_mfma_f32_16x16x32_f16 v[60:63], v[172:175], v[204:207], v[60:63]
	v_mfma_f32_16x16x32_f16 v[56:59], v[180:183], v[204:207], v[56:59]
	v_mfma_f32_16x16x32_f16 v[44:47], v[172:175], v[212:215], v[44:47]
	v_mfma_f32_16x16x32_f16 v[40:43], v[180:183], v[212:215], v[40:43]
	v_mfma_f32_16x16x32_f16 v[28:31], v[172:175], v[220:223], v[28:31]
	v_mfma_f32_16x16x32_f16 v[24:27], v[180:183], v[220:223], v[24:27]
	v_mfma_f32_16x16x32_f16 v[12:15], v[172:175], v[228:231], v[12:15]
	v_mfma_f32_16x16x32_f16 v[8:11], v[180:183], v[228:231], v[8:11]
	v_mfma_f32_16x16x32_f16 v[60:63], v[176:179], v[208:211], v[60:63]
	v_mfma_f32_16x16x32_f16 v[56:59], v[184:187], v[208:211], v[56:59]
	v_mfma_f32_16x16x32_f16 v[44:47], v[176:179], v[216:219], v[44:47]
	v_mfma_f32_16x16x32_f16 v[40:43], v[184:187], v[216:219], v[40:43]
	v_mfma_f32_16x16x32_f16 v[28:31], v[176:179], v[224:227], v[28:31]
	v_mfma_f32_16x16x32_f16 v[24:27], v[184:187], v[224:227], v[24:27]
	v_mfma_f32_16x16x32_f16 v[12:15], v[176:179], v[232:235], v[12:15]
	v_mfma_f32_16x16x32_f16 v[8:11], v[184:187], v[232:235], v[8:11]
	s_setprio 0
	s_setprio 1
	v_mfma_f32_16x16x32_f16 v[52:55], v[188:191], v[204:207], v[52:55]
	v_mfma_f32_16x16x32_f16 v[48:51], v[196:199], v[204:207], v[48:51]
	v_mfma_f32_16x16x32_f16 v[36:39], v[188:191], v[212:215], v[36:39]
	v_mfma_f32_16x16x32_f16 v[32:35], v[196:199], v[212:215], v[32:35]
	v_mfma_f32_16x16x32_f16 v[20:23], v[188:191], v[220:223], v[20:23]
	v_mfma_f32_16x16x32_f16 v[16:19], v[196:199], v[220:223], v[16:19]
	v_mfma_f32_16x16x32_f16 v[4:7], v[188:191], v[228:231], v[4:7]
	v_mfma_f32_16x16x32_f16 v[0:3], v[196:199], v[228:231], v[0:3]
	v_mfma_f32_16x16x32_f16 v[52:55], v[192:195], v[208:211], v[52:55]
	v_mfma_f32_16x16x32_f16 v[48:51], v[200:203], v[208:211], v[48:51]
	v_mfma_f32_16x16x32_f16 v[36:39], v[192:195], v[216:219], v[36:39]
	v_mfma_f32_16x16x32_f16 v[32:35], v[200:203], v[216:219], v[32:35]
	v_mfma_f32_16x16x32_f16 v[20:23], v[192:195], v[224:227], v[20:23]
	v_mfma_f32_16x16x32_f16 v[16:19], v[200:203], v[224:227], v[16:19]
	v_mfma_f32_16x16x32_f16 v[4:7], v[192:195], v[232:235], v[4:7]
	v_mfma_f32_16x16x32_f16 v[0:3], v[200:203], v[232:235], v[0:3]
	s_setprio 0
	s_barrier
	s_add_i32 s68, s68, 2
	s_add_u32 s8, s8, 0x100
	s_addc_u32 s9, s9, 0
	s_add_u32 s66, s66, 0x100
	s_addc_u32 s67, s67, 0
	s_cmp_gt_u32 s68, 13
